# move the solve-side partner barrier in P3 later so both wave halves are balanced around it
# speedup vs baseline: 1.0459x; 1.0096x over previous
.LBB0_416:
	s_andn2_saveexec_b64 s[6:7], s[6:7]
	s_cbranch_execz .LBB0_284
	v_cmp_gt_i32_e64 s[0:1], s96, v77
	v_add_u32_e32 v39, 0xffffff80, v77
	v_cmp_lt_i32_e32 vcc, s93, v77
	v_cndmask_b32_e64 v0, v65, v74, s[0:1]
	v_cndmask_b32_e64 v1, v39, v77, s[0:1]
	v_lshl_add_u32 v0, v1, 1, v0
	v_cndmask_b32_e64 v1, v75, v76, s[0:1]
	s_nop 0
	v_add_u32_e32 v11, 0, v1
	v_add_u32_e32 v10, 0, v0
	ds_read2_b32 v[0:1], v11 offset1:1
	ds_read_u16 v2, v10
	ds_read_u16 v8, v10 offset:272
	ds_read_u16 v9, v10 offset:544
	ds_read_u16 v12, v10 offset:816
	ds_read_u16 v13, v10 offset:1088
	ds_read_u16 v14, v10 offset:1360
	ds_read_u16 v15, v10 offset:1632
	ds_read_u16 v16, v10 offset:1904
	s_waitcnt lgkmcnt(7)
	v_lshlrev_b32_e32 v17, 16, v2
	ds_read2_b32 v[2:3], v11 offset0:2 offset1:3
	ds_read2_b32 v[4:5], v11 offset0:4 offset1:5
	ds_read2_b32 v[6:7], v11 offset0:6 offset1:7
	s_waitcnt lgkmcnt(9)
	v_lshlrev_b32_e32 v8, 16, v8
	v_mul_f32_e32 v1, v1, v8
	s_waitcnt lgkmcnt(8)
	v_lshlrev_b32_e32 v8, 16, v9
	s_waitcnt lgkmcnt(2)
	v_mul_f32_e32 v25, v2, v8
	v_lshlrev_b32_e32 v2, 16, v12
	v_mul_f32_e32 v27, v3, v2
	v_lshlrev_b32_e32 v2, 16, v13
	s_waitcnt lgkmcnt(1)
	v_mul_f32_e32 v170, v4, v2
	v_lshlrev_b32_e32 v2, 16, v14
	v_mul_f32_e32 v171, v5, v2
	v_lshlrev_b32_e32 v2, 16, v15
	s_waitcnt lgkmcnt(0)
	v_mul_f32_e32 v172, v6, v2
	v_lshlrev_b32_e32 v2, 16, v16
	v_mul_f32_e32 v0, v0, v17
	v_mul_f32_e32 v173, v7, v2
	ds_read2_b32 v[2:3], v11 offset0:8 offset1:9
	ds_read_u16 v4, v10 offset:2176
	ds_read_u16 v12, v10 offset:2448
	ds_read_u16 v13, v10 offset:2720
	ds_read_u16 v14, v10 offset:2992
	ds_read_u16 v15, v10 offset:3264
	ds_read_u16 v16, v10 offset:3536
	ds_read_u16 v17, v10 offset:3808
	ds_read_u16 v18, v10 offset:4080
	s_waitcnt lgkmcnt(7)
	v_lshlrev_b32_e32 v19, 16, v4
	ds_read2_b32 v[4:5], v11 offset0:10 offset1:11
	ds_read2_b32 v[6:7], v11 offset0:12 offset1:13
	ds_read2_b32 v[8:9], v11 offset0:14 offset1:15
	v_mul_f32_e32 v174, v2, v19
	s_waitcnt lgkmcnt(9)
	v_lshlrev_b32_e32 v2, 16, v12
	v_mul_f32_e32 v188, v3, v2
	s_waitcnt lgkmcnt(8)
	v_lshlrev_b32_e32 v2, 16, v13
	s_waitcnt lgkmcnt(2)
	v_mul_f32_e32 v189, v4, v2
	v_lshlrev_b32_e32 v2, 16, v14
	v_mul_f32_e32 v190, v5, v2
	v_lshlrev_b32_e32 v2, 16, v15
	s_waitcnt lgkmcnt(1)
	v_mul_f32_e32 v191, v6, v2
	v_lshlrev_b32_e32 v2, 16, v16
	v_mul_f32_e32 v192, v7, v2
	v_lshlrev_b32_e32 v2, 16, v17
	s_waitcnt lgkmcnt(0)
	v_mul_f32_e32 v193, v8, v2
	v_lshlrev_b32_e32 v2, 16, v18
	v_mul_f32_e32 v194, v9, v2
	ds_read2_b32 v[2:3], v11 offset0:16 offset1:17
	ds_read_u16 v4, v10 offset:4352
	ds_read_u16 v12, v10 offset:4624
	ds_read_u16 v13, v10 offset:4896
	ds_read_u16 v14, v10 offset:5168
	ds_read_u16 v15, v10 offset:5440
	ds_read_u16 v16, v10 offset:5712
	ds_read_u16 v17, v10 offset:5984
	ds_read_u16 v18, v10 offset:6256
	s_waitcnt lgkmcnt(7)
	v_lshlrev_b32_e32 v19, 16, v4
	ds_read2_b32 v[4:5], v11 offset0:18 offset1:19
	ds_read2_b32 v[6:7], v11 offset0:20 offset1:21
	ds_read2_b32 v[8:9], v11 offset0:22 offset1:23
	v_mul_f32_e32 v195, v2, v19
	s_waitcnt lgkmcnt(9)
	v_lshlrev_b32_e32 v2, 16, v12
	v_mul_f32_e32 v196, v3, v2
	s_waitcnt lgkmcnt(8)
	v_lshlrev_b32_e32 v2, 16, v13
	s_waitcnt lgkmcnt(2)
	v_mul_f32_e32 v197, v4, v2
	v_lshlrev_b32_e32 v2, 16, v14
	v_mul_f32_e32 v198, v5, v2
	v_lshlrev_b32_e32 v2, 16, v15
	s_waitcnt lgkmcnt(1)
	v_mul_f32_e32 v199, v6, v2
	v_lshlrev_b32_e32 v2, 16, v16
	v_mul_f32_e32 v42, v7, v2
	v_lshlrev_b32_e32 v2, 16, v17
	s_waitcnt lgkmcnt(0)
	v_mul_f32_e32 v43, v8, v2
	v_lshlrev_b32_e32 v2, 16, v18
	v_mul_f32_e32 v44, v9, v2
	ds_read2_b32 v[2:3], v11 offset0:24 offset1:25
	ds_read_u16 v4, v10 offset:6528
	ds_read_u16 v12, v10 offset:6800
	ds_read_u16 v13, v10 offset:7072
	ds_read_u16 v14, v10 offset:7344
	ds_read_u16 v15, v10 offset:7616
	ds_read_u16 v16, v10 offset:7888
	ds_read_u16 v17, v10 offset:8160
	ds_read_u16 v18, v10 offset:8432
	s_waitcnt lgkmcnt(7)
	v_lshlrev_b32_e32 v19, 16, v4
	ds_read2_b32 v[4:5], v11 offset0:26 offset1:27
	ds_read2_b32 v[6:7], v11 offset0:28 offset1:29
	ds_read2_b32 v[8:9], v11 offset0:30 offset1:31
	v_mul_f32_e32 v45, v2, v19
	s_waitcnt lgkmcnt(9)
	v_lshlrev_b32_e32 v2, 16, v12
	v_mul_f32_e32 v46, v3, v2
	s_waitcnt lgkmcnt(8)
	v_lshlrev_b32_e32 v2, 16, v13
	s_waitcnt lgkmcnt(2)
	v_mul_f32_e32 v47, v4, v2
	v_lshlrev_b32_e32 v2, 16, v14
	v_mul_f32_e32 v48, v5, v2
	v_lshlrev_b32_e32 v2, 16, v15
	s_waitcnt lgkmcnt(1)
	v_mul_f32_e32 v49, v6, v2
	v_lshlrev_b32_e32 v2, 16, v16
	v_mul_f32_e32 v50, v7, v2
	v_lshlrev_b32_e32 v2, 16, v17
	s_waitcnt lgkmcnt(0)
	v_mul_f32_e32 v51, v8, v2
	v_lshlrev_b32_e32 v2, 16, v18
	v_mul_f32_e32 v78, v9, v2
	ds_read2_b32 v[2:3], v11 offset0:32 offset1:33
	ds_read_u16 v4, v10 offset:8704
	ds_read_u16 v12, v10 offset:8976
	ds_read_u16 v13, v10 offset:9248
	ds_read_u16 v14, v10 offset:9520
	ds_read_u16 v15, v10 offset:9792
	ds_read_u16 v16, v10 offset:10064
	ds_read_u16 v17, v10 offset:10336
	ds_read_u16 v18, v10 offset:10608
	s_waitcnt lgkmcnt(7)
	v_lshlrev_b32_e32 v19, 16, v4
	ds_read2_b32 v[4:5], v11 offset0:34 offset1:35
	ds_read2_b32 v[6:7], v11 offset0:36 offset1:37
	ds_read2_b32 v[8:9], v11 offset0:38 offset1:39
	v_mul_f32_e32 v79, v2, v19
	s_waitcnt lgkmcnt(9)
	v_lshlrev_b32_e32 v2, 16, v12
	v_mul_f32_e32 v80, v3, v2
	s_waitcnt lgkmcnt(8)
	v_lshlrev_b32_e32 v2, 16, v13
	s_waitcnt lgkmcnt(2)
	v_mul_f32_e32 v81, v4, v2
	v_lshlrev_b32_e32 v2, 16, v14
	v_mul_f32_e32 v82, v5, v2
	v_lshlrev_b32_e32 v2, 16, v15
	s_waitcnt lgkmcnt(1)
	v_mul_f32_e32 v83, v6, v2
	v_lshlrev_b32_e32 v2, 16, v16
	v_mul_f32_e32 v85, v7, v2
	v_lshlrev_b32_e32 v2, 16, v17
	s_waitcnt lgkmcnt(0)
	v_mul_f32_e32 v87, v8, v2
	v_lshlrev_b32_e32 v2, 16, v18
	v_mul_f32_e32 v89, v9, v2
	ds_read2_b32 v[2:3], v11 offset0:40 offset1:41
	ds_read_u16 v4, v10 offset:10880
	ds_read_u16 v12, v10 offset:11152
	ds_read_u16 v13, v10 offset:11424
	ds_read_u16 v14, v10 offset:11696
	ds_read_u16 v15, v10 offset:11968
	ds_read_u16 v16, v10 offset:12240
	ds_read_u16 v17, v10 offset:12512
	ds_read_u16 v18, v10 offset:12784
	s_waitcnt lgkmcnt(7)
	v_lshlrev_b32_e32 v19, 16, v4
	ds_read2_b32 v[4:5], v11 offset0:42 offset1:43
	ds_read2_b32 v[6:7], v11 offset0:44 offset1:45
	ds_read2_b32 v[8:9], v11 offset0:46 offset1:47
	v_mul_f32_e32 v91, v2, v19
	s_waitcnt lgkmcnt(9)
	v_lshlrev_b32_e32 v2, 16, v12
	v_mul_f32_e32 v93, v3, v2
	s_waitcnt lgkmcnt(8)
	v_lshlrev_b32_e32 v2, 16, v13
	s_waitcnt lgkmcnt(2)
	v_mul_f32_e32 v96, v4, v2
	v_lshlrev_b32_e32 v2, 16, v14
	v_mul_f32_e32 v98, v5, v2
	v_lshlrev_b32_e32 v2, 16, v15
	s_waitcnt lgkmcnt(1)
	v_mul_f32_e32 v99, v6, v2
	v_lshlrev_b32_e32 v2, 16, v16
	v_mul_f32_e32 v97, v7, v2
	v_lshlrev_b32_e32 v2, 16, v17
	s_waitcnt lgkmcnt(0)
	v_mul_f32_e32 v94, v8, v2
	v_lshlrev_b32_e32 v2, 16, v18
	v_mul_f32_e32 v92, v9, v2
	ds_read2_b32 v[2:3], v11 offset0:48 offset1:49
	ds_read_u16 v4, v10 offset:13056
	ds_read_u16 v12, v10 offset:13328
	ds_read_u16 v13, v10 offset:13600
	ds_read_u16 v14, v10 offset:13872
	ds_read_u16 v15, v10 offset:14144
	ds_read_u16 v16, v10 offset:14416
	ds_read_u16 v17, v10 offset:14688
	ds_read_u16 v18, v10 offset:14960
	s_waitcnt lgkmcnt(7)
	v_lshlrev_b32_e32 v19, 16, v4
	ds_read2_b32 v[4:5], v11 offset0:50 offset1:51
	ds_read2_b32 v[6:7], v11 offset0:52 offset1:53
	ds_read2_b32 v[8:9], v11 offset0:54 offset1:55
	v_mul_f32_e32 v90, v2, v19
	s_waitcnt lgkmcnt(9)
	v_lshlrev_b32_e32 v2, 16, v12
	v_mul_f32_e32 v88, v3, v2
	s_waitcnt lgkmcnt(8)
	v_lshlrev_b32_e32 v2, 16, v13
	s_waitcnt lgkmcnt(2)
	v_mul_f32_e32 v86, v4, v2
	v_lshlrev_b32_e32 v2, 16, v14
	v_mul_f32_e32 v84, v5, v2
	v_lshlrev_b32_e32 v2, 16, v15
	s_waitcnt lgkmcnt(1)
	v_mul_f32_e32 v35, v6, v2
	v_lshlrev_b32_e32 v2, 16, v16
	v_mul_f32_e32 v34, v7, v2
	v_lshlrev_b32_e32 v2, 16, v17
	s_waitcnt lgkmcnt(0)
	v_mul_f32_e32 v33, v8, v2
	v_lshlrev_b32_e32 v2, 16, v18
	v_mul_f32_e32 v32, v9, v2
	ds_read2_b32 v[2:3], v11 offset0:56 offset1:57
	ds_read_u16 v4, v10 offset:15232
	ds_read_u16 v8, v10 offset:15504
	ds_read_u16 v9, v10 offset:15776
	ds_read_u16 v12, v10 offset:16048
	ds_read_u16 v13, v10 offset:16320
	ds_read_u16 v14, v10 offset:16592
	ds_read_u16 v15, v10 offset:16864
	ds_read_u16 v175, v10 offset:17136
	s_waitcnt lgkmcnt(7)
	v_lshlrev_b32_e32 v10, 16, v4
	ds_read2_b32 v[4:5], v11 offset0:58 offset1:59
	ds_read2_b32 v[6:7], v11 offset0:60 offset1:61
	ds_read2_b32 v[40:41], v11 offset0:62 offset1:63
	v_mul_f32_e32 v31, v2, v10
	s_waitcnt lgkmcnt(9)
	v_lshlrev_b32_e32 v2, 16, v8
	v_mul_f32_e32 v30, v3, v2
	s_waitcnt lgkmcnt(8)
	v_lshlrev_b32_e32 v2, 16, v9
	s_waitcnt lgkmcnt(2)
	v_mul_f32_e32 v29, v4, v2
	v_lshlrev_b32_e32 v2, 16, v12
	v_mul_f32_e32 v28, v5, v2
	v_lshlrev_b32_e32 v2, 16, v13
	s_waitcnt lgkmcnt(1)
	v_mul_f32_e32 v26, v6, v2
	v_lshlrev_b32_e32 v2, 16, v14
	v_mul_f32_e32 v24, v7, v2
	v_mov_b32 v2, 0
	v_lshlrev_b32_e32 v176, 16, v15
	v_lshl_add_u32 v95, v2, 2, 0
	ds_read_b128 v[2:5], v95 offset:52496
	s_waitcnt lgkmcnt(0)
	ds_read_b128 v[4:7], v95 offset:52768
	s_waitcnt lgkmcnt(0)
	ds_read_b128 v[6:9], v95 offset:53040
	ds_read_b128 v[100:103], v95 offset:53312
	ds_read_b128 v[104:107], v95 offset:53584
	ds_read_b128 v[10:13], v95 offset:53600
	ds_read_b128 v[108:111], v95 offset:53856
	s_waitcnt lgkmcnt(1)
	ds_read_b128 v[12:15], v95 offset:53872
	ds_read_b128 v[112:115], v95 offset:54128
	ds_read_b128 v[116:119], v95 offset:54144
	ds_read_b128 v[120:123], v95 offset:54400
	ds_read_b128 v[124:127], v95 offset:54416
	ds_read_b128 v[128:131], v95 offset:54672
	ds_read_b128 v[132:135], v95 offset:54688
	ds_read_b128 v[16:19], v95 offset:54704
	ds_read_b128 v[136:139], v95 offset:54944
	ds_read_b128 v[140:143], v95 offset:54960
	ds_read_b128 v[144:147], v95 offset:54976
	s_waitcnt lgkmcnt(0)
	ds_read_b128 v[146:149], v95 offset:55216
	ds_read_b128 v[150:153], v95 offset:55232
	ds_read_b128 v[154:157], v95 offset:55248
	ds_read_b128 v[158:161], v95 offset:55488
	ds_read_b128 v[162:165], v95 offset:55504
	ds_read_b128 v[166:169], v95 offset:55520
	v_lshlrev_b32_e32 v3, 16, v175
	v_mul_f32_e32 v17, v40, v176
	v_mul_f32_e32 v11, v41, v3
	v_add_u32_e32 v14, 0xcc00, v95
	v_fma_f32 v1, -v2, v0, v1
	v_fma_f32 v2, -v4, v0, v25
	v_fma_f32 v3, -v6, v0, v27
	v_fma_f32 v2, -v5, v1, v2
	v_fma_f32 v3, -v7, v1, v3
	v_fma_f32 v3, -v8, v2, v3
	v_fma_f32 v4, -v100, v0, v170
	v_fma_f32 v5, -v104, v0, v171
	v_fma_f32 v6, -v108, v0, v172
	v_fma_f32 v7, -v112, v0, v173
	v_fma_f32 v8, -v120, v0, v174
	v_fma_f32 v4, -v101, v1, v4
	v_fma_f32 v5, -v105, v1, v5
	v_fma_f32 v6, -v109, v1, v6
	v_fma_f32 v7, -v113, v1, v7
	v_fma_f32 v8, -v121, v1, v8
	v_fma_f32 v4, -v102, v2, v4
	v_fma_f32 v5, -v106, v2, v5
	v_fma_f32 v6, -v110, v2, v6
	v_fma_f32 v7, -v114, v2, v7
	v_fma_f32 v8, -v122, v2, v8
	v_fma_f32 v4, -v103, v3, v4
	v_fma_f32 v5, -v107, v3, v5
	v_fma_f32 v6, -v111, v3, v6
	v_fma_f32 v7, -v115, v3, v7
	v_fma_f32 v8, -v123, v3, v8
	v_fma_f32 v5, -v10, v4, v5
	v_fma_f32 v6, -v12, v4, v6
	v_fma_f32 v7, -v116, v4, v7
	v_fma_f32 v8, -v124, v4, v8
	v_fma_f32 v6, -v13, v5, v6
	v_fma_f32 v7, -v117, v5, v7
	v_fma_f32 v8, -v125, v5, v8
	v_fma_f32 v7, -v118, v6, v7
	v_fma_f32 v8, -v126, v6, v8
	v_fma_f32 v8, -v127, v7, v8
	ds_read_b128 v[100:103], v95 offset:55760
	ds_read_b128 v[104:107], v95 offset:55776
	ds_read_b128 v[108:111], v95 offset:55792
	ds_read_b128 v[112:115], v95 offset:55808
	s_waitcnt lgkmcnt(0)
	ds_read_b128 v[114:117], v95 offset:56032
	ds_read_b128 v[118:121], v95 offset:56048
	ds_read_b128 v[122:125], v95 offset:56064
	ds_read_b128 v[170:173], v95 offset:56080
	s_waitcnt lgkmcnt(0)
	ds_read_b128 v[172:175], v95 offset:56304
	ds_read_b128 v[176:179], v95 offset:56320
	ds_read_b128 v[180:183], v95 offset:56336
	ds_read_b128 v[184:187], v95 offset:56352
	v_fma_f32 v9, -v128, v0, v188
	v_fma_f32 v10, -v136, v0, v189
	v_fma_f32 v12, -v146, v0, v190
	v_fma_f32 v13, -v158, v0, v191
	v_fma_f32 v9, -v129, v1, v9
	v_fma_f32 v10, -v137, v1, v10
	v_fma_f32 v12, -v147, v1, v12
	v_fma_f32 v13, -v159, v1, v13
	v_fma_f32 v9, -v130, v2, v9
	v_fma_f32 v10, -v138, v2, v10
	v_fma_f32 v12, -v148, v2, v12
	v_fma_f32 v13, -v160, v2, v13
	v_fma_f32 v9, -v131, v3, v9
	v_fma_f32 v10, -v139, v3, v10
	v_fma_f32 v12, -v149, v3, v12
	v_fma_f32 v13, -v161, v3, v13
	v_fma_f32 v9, -v132, v4, v9
	v_fma_f32 v10, -v140, v4, v10
	v_fma_f32 v12, -v150, v4, v12
	v_fma_f32 v13, -v162, v4, v13
	v_fma_f32 v9, -v133, v5, v9
	v_fma_f32 v10, -v141, v5, v10
	v_fma_f32 v12, -v151, v5, v12
	v_fma_f32 v13, -v163, v5, v13
	v_fma_f32 v9, -v134, v6, v9
	v_fma_f32 v10, -v142, v6, v10
	v_fma_f32 v12, -v152, v6, v12
	v_fma_f32 v13, -v164, v6, v13
	v_fma_f32 v9, -v135, v7, v9
	v_fma_f32 v10, -v143, v7, v10
	v_fma_f32 v12, -v153, v7, v12
	v_fma_f32 v13, -v165, v7, v13
	v_fma_f32 v9, -v16, v8, v9
	v_fma_f32 v10, -v144, v8, v10
	v_fma_f32 v12, -v154, v8, v12
	v_fma_f32 v13, -v166, v8, v13
	v_fma_f32 v10, -v145, v9, v10
	v_fma_f32 v12, -v155, v9, v12
	v_fma_f32 v13, -v167, v9, v13
	v_fma_f32 v12, -v156, v10, v12
	v_fma_f32 v13, -v168, v10, v13
	v_fma_f32 v13, -v169, v12, v13
	ds_read_b128 v[126:129], v95 offset:56576
	ds_read_b128 v[130:133], v95 offset:56592
	ds_read_b128 v[134:137], v95 offset:56608
	ds_read_b128 v[138:141], v95 offset:56624
	ds_read_b128 v[142:145], v95 offset:56848
	ds_read_b128 v[146:149], v95 offset:56864
	ds_read_b128 v[150:153], v95 offset:56880
	ds_read_b128 v[154:157], v95 offset:56896
	ds_read_b128 v[158:161], v95 offset:56912
	s_waitcnt lgkmcnt(0)
	ds_read_b128 v[160:163], v95 offset:57120
	ds_read_b128 v[164:167], v95 offset:57136
	ds_read_b128 v[188:191], v95 offset:57152
	v_fma_f32 v15, -v100, v0, v192
	v_fma_f32 v16, -v114, v0, v193
	v_fma_f32 v18, -v172, v0, v194
	v_fma_f32 v15, -v101, v1, v15
	v_fma_f32 v16, -v115, v1, v16
	v_fma_f32 v18, -v173, v1, v18
	v_fma_f32 v15, -v102, v2, v15
	v_fma_f32 v16, -v116, v2, v16
	v_fma_f32 v18, -v174, v2, v18
	v_fma_f32 v15, -v103, v3, v15
	v_fma_f32 v16, -v117, v3, v16
	v_fma_f32 v18, -v175, v3, v18
	v_fma_f32 v15, -v104, v4, v15
	v_fma_f32 v16, -v118, v4, v16
	v_fma_f32 v18, -v176, v4, v18
	v_fma_f32 v15, -v105, v5, v15
	v_fma_f32 v16, -v119, v5, v16
	v_fma_f32 v18, -v177, v5, v18
	v_fma_f32 v15, -v106, v6, v15
	v_fma_f32 v16, -v120, v6, v16
	v_fma_f32 v18, -v178, v6, v18
	v_fma_f32 v15, -v107, v7, v15
	v_fma_f32 v16, -v121, v7, v16
	v_fma_f32 v18, -v179, v7, v18
	v_fma_f32 v15, -v108, v8, v15
	v_fma_f32 v16, -v122, v8, v16
	v_fma_f32 v18, -v180, v8, v18
	v_fma_f32 v15, -v109, v9, v15
	v_fma_f32 v16, -v123, v9, v16
	v_fma_f32 v18, -v181, v9, v18
	v_fma_f32 v15, -v110, v10, v15
	v_fma_f32 v16, -v124, v10, v16
	v_fma_f32 v18, -v182, v10, v18
	v_fma_f32 v15, -v111, v12, v15
	v_fma_f32 v16, -v125, v12, v16
	v_fma_f32 v18, -v183, v12, v18
	v_fma_f32 v15, -v112, v13, v15
	v_fma_f32 v16, -v170, v13, v16
	v_fma_f32 v18, -v184, v13, v18
	v_fma_f32 v16, -v171, v15, v16
	v_fma_f32 v18, -v185, v15, v18
	v_fma_f32 v18, -v186, v16, v18
	ds_read_b128 v[100:103], v95 offset:57168
	ds_read_b128 v[104:107], v95 offset:57184
	s_waitcnt lgkmcnt(0)
	ds_read_b128 v[106:109], v95 offset:57392
	ds_read_b128 v[110:113], v95 offset:57408
	ds_read_b128 v[114:117], v95 offset:57424
	ds_read_b128 v[118:121], v95 offset:57440
	ds_read_b128 v[122:125], v95 offset:57456
	ds_read_b128 v[168:171], v95 offset:57664
	ds_read_b128 v[172:175], v95 offset:57680
	ds_read_b128 v[176:179], v95 offset:57696
	ds_read_b128 v[180:183], v95 offset:57712
	ds_read_b128 v[184:187], v95 offset:57728
	v_fma_f32 v19, -v126, v0, v195
	v_fma_f32 v25, -v142, v0, v196
	v_fma_f32 v19, -v127, v1, v19
	v_fma_f32 v25, -v143, v1, v25
	v_fma_f32 v19, -v128, v2, v19
	v_fma_f32 v25, -v144, v2, v25
	v_fma_f32 v19, -v129, v3, v19
	v_fma_f32 v25, -v145, v3, v25
	v_fma_f32 v19, -v130, v4, v19
	v_fma_f32 v25, -v146, v4, v25
	v_fma_f32 v19, -v131, v5, v19
	v_fma_f32 v25, -v147, v5, v25
	v_fma_f32 v27, -v160, v0, v197
	v_fma_f32 v19, -v132, v6, v19
	v_fma_f32 v25, -v148, v6, v25
	v_fma_f32 v27, -v161, v1, v27
	v_fma_f32 v19, -v133, v7, v19
	v_fma_f32 v25, -v149, v7, v25
	v_fma_f32 v27, -v162, v2, v27
	v_fma_f32 v19, -v134, v8, v19
	v_fma_f32 v25, -v150, v8, v25
	v_fma_f32 v27, -v163, v3, v27
	v_fma_f32 v19, -v135, v9, v19
	v_fma_f32 v25, -v151, v9, v25
	v_fma_f32 v27, -v164, v4, v27
	v_fma_f32 v19, -v136, v10, v19
	v_fma_f32 v25, -v152, v10, v25
	v_fma_f32 v27, -v165, v5, v27
	v_fma_f32 v19, -v137, v12, v19
	v_fma_f32 v25, -v153, v12, v25
	v_fma_f32 v27, -v166, v6, v27
	v_fma_f32 v19, -v138, v13, v19
	v_fma_f32 v25, -v154, v13, v25
	v_fma_f32 v27, -v167, v7, v27
	v_fma_f32 v19, -v139, v15, v19
	v_fma_f32 v25, -v155, v15, v25
	v_fma_f32 v27, -v188, v8, v27
	v_fma_f32 v19, -v140, v16, v19
	v_fma_f32 v25, -v156, v16, v25
	v_fma_f32 v27, -v189, v9, v27
	v_fma_f32 v19, -v141, v18, v19
	v_fma_f32 v25, -v157, v18, v25
	v_fma_f32 v27, -v190, v10, v27
	v_fma_f32 v25, -v158, v19, v25
	v_fma_f32 v27, -v191, v12, v27
	ds_read_b128 v[126:129], v95 offset:57936
	ds_read_b128 v[130:133], v95 offset:57952
	ds_read_b128 v[134:137], v95 offset:57968
	ds_read_b128 v[138:141], v95 offset:57984
	ds_read_b128 v[142:145], v95 offset:58000
	ds_read_b128 v[146:149], v95 offset:58016
	s_waitcnt lgkmcnt(0)
	ds_read_b128 v[148:151], v95 offset:58208
	ds_read_b128 v[152:155], v95 offset:58224
	ds_read_b128 v[156:159], v95 offset:58240
	ds_read_b128 v[160:163], v95 offset:58256
	ds_read_b128 v[164:167], v95 offset:58272
	ds_read_b128 v[188:191], v95 offset:58288
	v_fma_f32 v40, -v106, v0, v198
	v_fma_f32 v41, -v168, v0, v199
	v_fma_f32 v40, -v107, v1, v40
	v_fma_f32 v41, -v169, v1, v41
	v_fma_f32 v40, -v108, v2, v40
	v_fma_f32 v41, -v170, v2, v41
	v_fma_f32 v40, -v109, v3, v40
	v_fma_f32 v41, -v171, v3, v41
	v_fma_f32 v40, -v110, v4, v40
	v_fma_f32 v41, -v172, v4, v41
	v_fma_f32 v40, -v111, v5, v40
	v_fma_f32 v41, -v173, v5, v41
	v_fma_f32 v40, -v112, v6, v40
	v_fma_f32 v41, -v174, v6, v41
	v_fma_f32 v40, -v113, v7, v40
	v_fma_f32 v41, -v175, v7, v41
	v_fma_f32 v40, -v114, v8, v40
	v_fma_f32 v41, -v176, v8, v41
	v_fma_f32 v40, -v115, v9, v40
	v_fma_f32 v41, -v177, v9, v41
	v_fma_f32 v40, -v116, v10, v40
	v_fma_f32 v41, -v178, v10, v41
	v_fma_f32 v40, -v117, v12, v40
	v_fma_f32 v41, -v179, v12, v41
	v_fma_f32 v27, -v100, v13, v27
	v_fma_f32 v40, -v118, v13, v40
	v_fma_f32 v41, -v180, v13, v41
	v_fma_f32 v27, -v101, v15, v27
	v_fma_f32 v40, -v119, v15, v40
	v_fma_f32 v41, -v181, v15, v41
	v_fma_f32 v27, -v102, v16, v27
	v_fma_f32 v40, -v120, v16, v40
	v_fma_f32 v41, -v182, v16, v41
	v_fma_f32 v27, -v103, v18, v27
	v_fma_f32 v40, -v121, v18, v40
	v_fma_f32 v41, -v183, v18, v41
	v_fma_f32 v27, -v104, v19, v27
	v_fma_f32 v40, -v122, v19, v40
	v_fma_f32 v41, -v184, v19, v41
	v_fma_f32 v27, -v105, v25, v27
	v_fma_f32 v40, -v123, v25, v40
	v_fma_f32 v41, -v185, v25, v41
	v_fma_f32 v40, -v124, v27, v40
	v_fma_f32 v41, -v186, v27, v41
	v_fma_f32 v41, -v187, v40, v41
	ds_read_b128 v[100:103], v95 offset:58480
	ds_read_b128 v[104:107], v95 offset:58496
	ds_read_b128 v[108:111], v95 offset:58512
	ds_read_b128 v[112:115], v95 offset:58528
	ds_read_b128 v[116:119], v95 offset:58544
	ds_read_b128 v[120:123], v95 offset:58560
	ds_read_b128 v[168:171], v95 offset:58752
	ds_read_b128 v[172:175], v95 offset:58768
	ds_read_b128 v[176:179], v95 offset:58784
	ds_read_b128 v[180:183], v95 offset:58800
	ds_read_b128 v[184:187], v95 offset:58816
	s_waitcnt lgkmcnt(11)
	ds_read_b128 v[190:193], v95 offset:58832
	v_fma_f32 v42, -v126, v0, v42
	v_fma_f32 v43, -v148, v0, v43
	v_fma_f32 v42, -v127, v1, v42
	v_fma_f32 v43, -v149, v1, v43
	v_fma_f32 v42, -v128, v2, v42
	v_fma_f32 v43, -v150, v2, v43
	v_fma_f32 v42, -v129, v3, v42
	v_fma_f32 v43, -v151, v3, v43
	v_fma_f32 v42, -v130, v4, v42
	v_fma_f32 v43, -v152, v4, v43
	v_fma_f32 v42, -v131, v5, v42
	v_fma_f32 v43, -v153, v5, v43
	v_fma_f32 v42, -v132, v6, v42
	v_fma_f32 v43, -v154, v6, v43
	v_fma_f32 v42, -v133, v7, v42
	v_fma_f32 v43, -v155, v7, v43
	v_fma_f32 v42, -v134, v8, v42
	v_fma_f32 v43, -v156, v8, v43
	v_fma_f32 v42, -v135, v9, v42
	v_fma_f32 v43, -v157, v9, v43
	v_fma_f32 v42, -v136, v10, v42
	v_fma_f32 v43, -v158, v10, v43
	v_fma_f32 v42, -v137, v12, v42
	v_fma_f32 v43, -v159, v12, v43
	v_fma_f32 v42, -v138, v13, v42
	v_fma_f32 v43, -v160, v13, v43
	v_fma_f32 v42, -v139, v15, v42
	v_fma_f32 v43, -v161, v15, v43
	v_fma_f32 v42, -v140, v16, v42
	v_fma_f32 v43, -v162, v16, v43
	v_fma_f32 v42, -v141, v18, v42
	v_fma_f32 v43, -v163, v18, v43
	v_fma_f32 v42, -v142, v19, v42
	v_fma_f32 v43, -v164, v19, v43
	v_fma_f32 v42, -v143, v25, v42
	v_fma_f32 v43, -v165, v25, v43
	v_fma_f32 v42, -v144, v27, v42
	v_fma_f32 v43, -v166, v27, v43
	v_fma_f32 v42, -v145, v40, v42
	v_fma_f32 v43, -v167, v40, v43
	v_fma_f32 v42, -v146, v41, v42
	v_fma_f32 v43, -v188, v41, v43
	v_fma_f32 v43, -v189, v42, v43
	ds_read_b128 v[124:127], v95 offset:59024
	ds_read_b128 v[128:131], v95 offset:59040
	ds_read_b128 v[132:135], v95 offset:59056
	ds_read_b128 v[136:139], v95 offset:59072
	ds_read_b128 v[140:143], v95 offset:59088
	ds_read_b128 v[144:147], v95 offset:59104
	ds_read_b128 v[148:151], v95 offset:59120
	s_waitcnt lgkmcnt(0)
	ds_read_b128 v[150:153], v95 offset:59296
	ds_read_b128 v[154:157], v95 offset:59312
	ds_read_b128 v[158:161], v95 offset:59328
	ds_read_b128 v[162:165], v95 offset:59344
	ds_read_b128 v[194:197], v95 offset:59360
	v_fma_f32 v44, -v100, v0, v44
	v_fma_f32 v45, -v168, v0, v45
	v_fma_f32 v44, -v101, v1, v44
	v_fma_f32 v45, -v169, v1, v45
	v_fma_f32 v44, -v102, v2, v44
	v_fma_f32 v45, -v170, v2, v45
	v_fma_f32 v44, -v103, v3, v44
	v_fma_f32 v45, -v171, v3, v45
	v_fma_f32 v44, -v104, v4, v44
	v_fma_f32 v45, -v172, v4, v45
	v_fma_f32 v44, -v105, v5, v44
	v_fma_f32 v45, -v173, v5, v45
	v_fma_f32 v44, -v106, v6, v44
	v_fma_f32 v45, -v174, v6, v45
	v_fma_f32 v44, -v107, v7, v44
	v_fma_f32 v45, -v175, v7, v45
	v_fma_f32 v44, -v108, v8, v44
	v_fma_f32 v45, -v176, v8, v45
	v_fma_f32 v44, -v109, v9, v44
	v_fma_f32 v45, -v177, v9, v45
	v_fma_f32 v44, -v110, v10, v44
	v_fma_f32 v45, -v178, v10, v45
	v_fma_f32 v44, -v111, v12, v44
	v_fma_f32 v45, -v179, v12, v45
	v_fma_f32 v44, -v112, v13, v44
	v_fma_f32 v45, -v180, v13, v45
	v_fma_f32 v44, -v113, v15, v44
	v_fma_f32 v45, -v181, v15, v45
	v_fma_f32 v44, -v114, v16, v44
	v_fma_f32 v45, -v182, v16, v45
	v_fma_f32 v44, -v115, v18, v44
	v_fma_f32 v45, -v183, v18, v45
	v_fma_f32 v44, -v116, v19, v44
	v_fma_f32 v45, -v184, v19, v45
	v_fma_f32 v44, -v117, v25, v44
	v_fma_f32 v45, -v185, v25, v45
	v_fma_f32 v44, -v118, v27, v44
	v_fma_f32 v45, -v186, v27, v45
	v_fma_f32 v44, -v119, v40, v44
	v_fma_f32 v45, -v187, v40, v45
	v_fma_f32 v44, -v120, v41, v44
	v_fma_f32 v45, -v190, v41, v45
	v_fma_f32 v44, -v121, v42, v44
	v_fma_f32 v45, -v191, v42, v45
	v_fma_f32 v44, -v122, v43, v44
	v_fma_f32 v45, -v192, v43, v45
	v_fma_f32 v45, -v193, v44, v45
	ds_read_b128 v[100:103], v95 offset:59376
	ds_read_b128 v[104:107], v95 offset:59392
	s_waitcnt lgkmcnt(0)
	ds_read_b128 v[106:109], v95 offset:59568
	ds_read_b128 v[110:113], v95 offset:59584
	ds_read_b128 v[114:117], v95 offset:59600
	ds_read_b128 v[118:121], v95 offset:59616
	ds_read_b128 v[166:169], v95 offset:59632
	ds_read_b128 v[170:173], v95 offset:59648
	ds_read_b128 v[174:177], v95 offset:59664
	ds_read_b128 v[178:181], v95 offset:59840
	ds_read_b128 v[182:185], v95 offset:59856
	ds_read_b128 v[186:189], v95 offset:59872
	v_fma_f32 v46, -v124, v0, v46
	v_fma_f32 v46, -v125, v1, v46
	v_fma_f32 v46, -v126, v2, v46
	v_fma_f32 v46, -v127, v3, v46
	v_fma_f32 v46, -v128, v4, v46
	v_fma_f32 v46, -v129, v5, v46
	v_fma_f32 v47, -v150, v0, v47
	v_fma_f32 v46, -v130, v6, v46
	v_fma_f32 v47, -v151, v1, v47
	v_fma_f32 v46, -v131, v7, v46
	v_fma_f32 v47, -v152, v2, v47
	v_fma_f32 v46, -v132, v8, v46
	v_fma_f32 v47, -v153, v3, v47
	v_fma_f32 v46, -v133, v9, v46
	v_fma_f32 v47, -v154, v4, v47
	v_fma_f32 v46, -v134, v10, v46
	v_fma_f32 v47, -v155, v5, v47
	v_fma_f32 v46, -v135, v12, v46
	v_fma_f32 v47, -v156, v6, v47
	v_fma_f32 v46, -v136, v13, v46
	v_fma_f32 v47, -v157, v7, v47
	v_fma_f32 v46, -v137, v15, v46
	v_fma_f32 v47, -v158, v8, v47
	v_fma_f32 v46, -v138, v16, v46
	v_fma_f32 v47, -v159, v9, v47
	v_fma_f32 v46, -v139, v18, v46
	v_fma_f32 v47, -v160, v10, v47
	v_fma_f32 v46, -v140, v19, v46
	v_fma_f32 v47, -v161, v12, v47
	v_fma_f32 v46, -v141, v25, v46
	v_fma_f32 v47, -v162, v13, v47
	v_fma_f32 v46, -v142, v27, v46
	v_fma_f32 v47, -v163, v15, v47
	v_fma_f32 v46, -v143, v40, v46
	v_fma_f32 v47, -v164, v16, v47
	v_fma_f32 v46, -v144, v41, v46
	v_fma_f32 v47, -v165, v18, v47
	v_fma_f32 v46, -v145, v42, v46
	v_fma_f32 v47, -v194, v19, v47
	v_fma_f32 v46, -v146, v43, v46
	v_fma_f32 v47, -v195, v25, v47
	v_fma_f32 v46, -v147, v44, v46
	v_fma_f32 v47, -v196, v27, v47
	v_fma_f32 v46, -v148, v45, v46
	v_fma_f32 v47, -v197, v40, v47
	ds_read_b128 v[122:125], v95 offset:59888
	ds_read_b128 v[126:129], v95 offset:59904
	ds_read_b128 v[130:133], v95 offset:59920
	ds_read_b128 v[134:137], v95 offset:59936
	ds_read_b128 v[138:141], v95 offset:60112
	ds_read_b128 v[142:145], v95 offset:60128
	ds_read_b128 v[146:149], v95 offset:60144
	ds_read_b128 v[150:153], v95 offset:60160
	ds_read_b128 v[154:157], v95 offset:60176
	ds_read_b128 v[158:161], v95 offset:60192
	ds_read_b128 v[162:165], v95 offset:60208
	ds_read_b128 v[190:193], v95 offset:60224
	s_waitcnt lgkmcnt(14)
	v_fma_f32 v48, -v106, v0, v48
	v_fma_f32 v48, -v107, v1, v48
	v_fma_f32 v48, -v108, v2, v48
	v_fma_f32 v48, -v109, v3, v48
	v_fma_f32 v48, -v110, v4, v48
	v_fma_f32 v48, -v111, v5, v48
	v_fma_f32 v48, -v112, v6, v48
	v_fma_f32 v48, -v113, v7, v48
	v_fma_f32 v48, -v114, v8, v48
	v_fma_f32 v48, -v115, v9, v48
	v_fma_f32 v48, -v116, v10, v48
	v_fma_f32 v48, -v117, v12, v48
	v_fma_f32 v48, -v118, v13, v48
	v_fma_f32 v48, -v119, v15, v48
	v_fma_f32 v48, -v120, v16, v48
	v_fma_f32 v48, -v121, v18, v48
	v_fma_f32 v49, -v178, v0, v49
	v_fma_f32 v48, -v166, v19, v48
	v_fma_f32 v49, -v179, v1, v49
	v_fma_f32 v48, -v167, v25, v48
	v_fma_f32 v49, -v180, v2, v49
	v_fma_f32 v48, -v168, v27, v48
	v_fma_f32 v49, -v181, v3, v49
	v_fma_f32 v48, -v169, v40, v48
	s_waitcnt lgkmcnt(13)
	v_fma_f32 v49, -v182, v4, v49
	v_fma_f32 v47, -v100, v41, v47
	v_fma_f32 v48, -v170, v41, v48
	v_fma_f32 v49, -v183, v5, v49
	v_fma_f32 v47, -v101, v42, v47
	v_fma_f32 v48, -v171, v42, v48
	v_fma_f32 v49, -v184, v6, v49
	v_fma_f32 v47, -v102, v43, v47
	v_fma_f32 v48, -v172, v43, v48
	v_fma_f32 v49, -v185, v7, v49
	v_fma_f32 v47, -v103, v44, v47
	v_fma_f32 v48, -v173, v44, v48
	s_waitcnt lgkmcnt(12)
	v_fma_f32 v49, -v186, v8, v49
	v_fma_f32 v47, -v104, v45, v47
	v_fma_f32 v48, -v174, v45, v48
	v_fma_f32 v49, -v187, v9, v49
	v_fma_f32 v47, -v105, v46, v47
	v_fma_f32 v48, -v175, v46, v48
	v_fma_f32 v49, -v188, v10, v49
	v_fma_f32 v48, -v176, v47, v48
	v_fma_f32 v49, -v189, v12, v49
	ds_read_b128 v[100:103], v95 offset:60384
	ds_read_b128 v[104:107], v95 offset:60400
	ds_read_b128 v[108:111], v95 offset:60416
	ds_read_b128 v[112:115], v95 offset:60432
	ds_read_b128 v[116:119], v95 offset:60448
	ds_read_b128 v[166:169], v95 offset:60464
	ds_read_b128 v[170:173], v95 offset:60480
	ds_read_b128 v[174:177], v95 offset:60496
	s_waitcnt lgkmcnt(0)
	ds_read_b128 v[176:179], v95 offset:60656
	ds_read_b128 v[180:183], v95 offset:60672
	ds_read_b128 v[184:187], v95 offset:60688
	ds_read_b128 v[192:195], v95 offset:60704
	v_fma_f32 v50, -v138, v0, v50
	v_fma_f32 v50, -v139, v1, v50
	v_fma_f32 v50, -v140, v2, v50
	v_fma_f32 v50, -v141, v3, v50
	v_fma_f32 v50, -v142, v4, v50
	v_fma_f32 v50, -v143, v5, v50
	v_fma_f32 v50, -v144, v6, v50
	v_fma_f32 v50, -v145, v7, v50
	v_fma_f32 v50, -v146, v8, v50
	v_fma_f32 v50, -v147, v9, v50
	v_fma_f32 v50, -v148, v10, v50
	v_fma_f32 v50, -v149, v12, v50
	v_fma_f32 v49, -v122, v13, v49
	v_fma_f32 v50, -v150, v13, v50
	v_fma_f32 v49, -v123, v15, v49
	v_fma_f32 v50, -v151, v15, v50
	v_fma_f32 v49, -v124, v16, v49
	v_fma_f32 v50, -v152, v16, v50
	v_fma_f32 v49, -v125, v18, v49
	v_fma_f32 v50, -v153, v18, v50
	v_fma_f32 v49, -v126, v19, v49
	v_fma_f32 v50, -v154, v19, v50
	v_fma_f32 v49, -v127, v25, v49
	v_fma_f32 v50, -v155, v25, v50
	v_fma_f32 v49, -v128, v27, v49
	v_fma_f32 v50, -v156, v27, v50
	v_fma_f32 v49, -v129, v40, v49
	v_fma_f32 v50, -v157, v40, v50
	v_fma_f32 v49, -v130, v41, v49
	v_fma_f32 v50, -v158, v41, v50
	v_fma_f32 v49, -v131, v42, v49
	v_fma_f32 v50, -v159, v42, v50
	v_fma_f32 v49, -v132, v43, v49
	v_fma_f32 v50, -v160, v43, v50
	v_fma_f32 v49, -v133, v44, v49
	v_fma_f32 v50, -v161, v44, v50
	v_fma_f32 v49, -v134, v45, v49
	v_fma_f32 v50, -v162, v45, v50
	v_fma_f32 v49, -v135, v46, v49
	v_fma_f32 v50, -v163, v46, v50
	v_fma_f32 v49, -v136, v47, v49
	v_fma_f32 v50, -v164, v47, v50
	v_fma_f32 v49, -v137, v48, v49
	v_fma_f32 v50, -v165, v48, v50
	v_fma_f32 v50, -v190, v49, v50
	ds_read_b128 v[120:123], v95 offset:60720
	ds_read_b128 v[124:127], v95 offset:60736
	ds_read_b128 v[128:131], v95 offset:60752
	ds_read_b128 v[132:135], v95 offset:60768
	ds_read_b128 v[136:139], v95 offset:60928
	ds_read_b128 v[140:143], v95 offset:60944
	ds_read_b128 v[144:147], v95 offset:60960
	ds_read_b128 v[148:151], v95 offset:60976
	ds_read_b128 v[152:155], v95 offset:60992
	ds_read_b128 v[156:159], v95 offset:61008
	ds_read_b128 v[160:163], v95 offset:61024
	ds_read_b128 v[188:191], v95 offset:61040
	v_fma_f32 v51, -v100, v0, v51
	v_fma_f32 v51, -v101, v1, v51
	v_fma_f32 v51, -v102, v2, v51
	v_fma_f32 v51, -v103, v3, v51
	v_fma_f32 v51, -v104, v4, v51
	v_fma_f32 v51, -v105, v5, v51
	v_fma_f32 v51, -v106, v6, v51
	v_fma_f32 v51, -v107, v7, v51
	v_fma_f32 v51, -v108, v8, v51
	v_fma_f32 v51, -v109, v9, v51
	v_fma_f32 v51, -v110, v10, v51
	v_fma_f32 v51, -v111, v12, v51
	v_fma_f32 v51, -v112, v13, v51
	v_fma_f32 v51, -v113, v15, v51
	v_fma_f32 v51, -v114, v16, v51
	s_waitcnt lgkmcnt(14)
	v_fma_f32 v78, -v176, v0, v78
	v_fma_f32 v51, -v115, v18, v51
	v_fma_f32 v78, -v177, v1, v78
	v_fma_f32 v51, -v116, v19, v51
	v_fma_f32 v78, -v178, v2, v78
	v_fma_f32 v51, -v117, v25, v51
	v_fma_f32 v78, -v179, v3, v78
	v_fma_f32 v51, -v118, v27, v51
	v_fma_f32 v78, -v180, v4, v78
	v_fma_f32 v51, -v119, v40, v51
	v_fma_f32 v78, -v181, v5, v78
	v_fma_f32 v51, -v166, v41, v51
	v_fma_f32 v78, -v182, v6, v78
	v_fma_f32 v51, -v167, v42, v51
	v_fma_f32 v78, -v183, v7, v78
	v_fma_f32 v51, -v168, v43, v51
	s_waitcnt lgkmcnt(13)
	v_fma_f32 v78, -v184, v8, v78
	v_fma_f32 v51, -v169, v44, v51
	v_fma_f32 v78, -v185, v9, v78
	v_fma_f32 v51, -v170, v45, v51
	v_fma_f32 v78, -v186, v10, v78
	v_fma_f32 v51, -v171, v46, v51
	v_fma_f32 v78, -v187, v12, v78
	v_fma_f32 v51, -v172, v47, v51
	s_waitcnt lgkmcnt(12)
	v_fma_f32 v78, -v192, v13, v78
	v_fma_f32 v51, -v173, v48, v51
	v_fma_f32 v78, -v193, v15, v78
	v_fma_f32 v51, -v174, v49, v51
	v_fma_f32 v78, -v194, v16, v78
	v_fma_f32 v51, -v175, v50, v51
	v_fma_f32 v78, -v195, v18, v78
	ds_read_b128 v[100:103], v95 offset:61200
	ds_read_b128 v[104:107], v95 offset:61216
	ds_read_b128 v[108:111], v95 offset:61232
	ds_read_b128 v[112:115], v95 offset:61248
	ds_read_b128 v[116:119], v95 offset:61264
	ds_read_b128 v[164:167], v95 offset:61280
	ds_read_b128 v[168:171], v95 offset:61296
	ds_read_b128 v[172:175], v95 offset:61312
	ds_read_b128 v[176:179], v95 offset:61328
	s_waitcnt lgkmcnt(0)
	ds_read_b128 v[178:181], v95 offset:61472
	ds_read_b128 v[182:185], v95 offset:61488
	ds_read_b128 v[192:195], v95 offset:61504
	v_fma_f32 v79, -v136, v0, v79
	v_fma_f32 v79, -v137, v1, v79
	v_fma_f32 v79, -v138, v2, v79
	v_fma_f32 v79, -v139, v3, v79
	v_fma_f32 v79, -v140, v4, v79
	v_fma_f32 v79, -v141, v5, v79
	v_fma_f32 v79, -v142, v6, v79
	v_fma_f32 v79, -v143, v7, v79
	v_fma_f32 v79, -v144, v8, v79
	v_fma_f32 v79, -v145, v9, v79
	v_fma_f32 v79, -v146, v10, v79
	v_fma_f32 v79, -v147, v12, v79
	v_fma_f32 v79, -v148, v13, v79
	v_fma_f32 v79, -v149, v15, v79
	v_fma_f32 v79, -v150, v16, v79
	v_fma_f32 v79, -v151, v18, v79
	v_fma_f32 v78, -v120, v19, v78
	v_fma_f32 v79, -v152, v19, v79
	v_fma_f32 v78, -v121, v25, v78
	v_fma_f32 v79, -v153, v25, v79
	v_fma_f32 v78, -v122, v27, v78
	v_fma_f32 v79, -v154, v27, v79
	v_fma_f32 v78, -v123, v40, v78
	v_fma_f32 v79, -v155, v40, v79
	v_fma_f32 v78, -v124, v41, v78
	v_fma_f32 v79, -v156, v41, v79
	v_fma_f32 v78, -v125, v42, v78
	v_fma_f32 v79, -v157, v42, v79
	v_fma_f32 v78, -v126, v43, v78
	v_fma_f32 v79, -v158, v43, v79
	v_fma_f32 v78, -v127, v44, v78
	v_fma_f32 v79, -v159, v44, v79
	v_fma_f32 v78, -v128, v45, v78
	v_fma_f32 v79, -v160, v45, v79
	v_fma_f32 v78, -v129, v46, v78
	v_fma_f32 v79, -v161, v46, v79
	v_fma_f32 v78, -v130, v47, v78
	v_fma_f32 v79, -v162, v47, v79
	v_fma_f32 v78, -v131, v48, v78
	v_fma_f32 v79, -v163, v48, v79
	v_fma_f32 v78, -v132, v49, v78
	v_fma_f32 v79, -v188, v49, v79
	v_fma_f32 v78, -v133, v50, v78
	v_fma_f32 v79, -v189, v50, v79
	v_fma_f32 v78, -v134, v51, v78
	v_fma_f32 v79, -v190, v51, v79
	v_fma_f32 v79, -v191, v78, v79
	s_waitcnt lgkmcnt(0)
	ds_read_b128 v[120:123], v95 offset:61520
	ds_read_b128 v[124:127], v95 offset:61536
	ds_read_b128 v[128:131], v95 offset:61552
	ds_read_b128 v[132:135], v95 offset:61568
	ds_read_b128 v[136:139], v95 offset:61584
	ds_read_b128 v[140:143], v95 offset:61600
	s_waitcnt lgkmcnt(0)
	ds_read_b128 v[142:145], v95 offset:61744
	ds_read_b128 v[146:149], v95 offset:61760
	ds_read_b128 v[150:153], v95 offset:61776
	ds_read_b128 v[154:157], v95 offset:61792
	ds_read_b128 v[158:161], v95 offset:61808
	ds_read_b128 v[186:189], v95 offset:61824
	v_fma_f32 v80, -v100, v0, v80
	v_fma_f32 v80, -v101, v1, v80
	v_fma_f32 v80, -v102, v2, v80
	v_fma_f32 v80, -v103, v3, v80
	v_fma_f32 v80, -v104, v4, v80
	v_fma_f32 v80, -v105, v5, v80
	v_fma_f32 v80, -v106, v6, v80
	v_fma_f32 v80, -v107, v7, v80
	v_fma_f32 v80, -v108, v8, v80
	v_fma_f32 v80, -v109, v9, v80
	v_fma_f32 v80, -v110, v10, v80
	v_fma_f32 v80, -v111, v12, v80
	v_fma_f32 v80, -v112, v13, v80
	v_fma_f32 v80, -v113, v15, v80
	v_fma_f32 v80, -v114, v16, v80
	v_fma_f32 v80, -v115, v18, v80
	v_fma_f32 v80, -v116, v19, v80
	v_fma_f32 v80, -v117, v25, v80
	v_fma_f32 v80, -v118, v27, v80
	v_fma_f32 v80, -v119, v40, v80
	v_fma_f32 v80, -v164, v41, v80
	v_fma_f32 v80, -v165, v42, v80
	v_fma_f32 v81, -v178, v0, v81
	v_fma_f32 v80, -v166, v43, v80
	v_fma_f32 v81, -v179, v1, v81
	v_fma_f32 v80, -v167, v44, v80
	v_fma_f32 v81, -v180, v2, v81
	v_fma_f32 v80, -v168, v45, v80
	v_fma_f32 v81, -v181, v3, v81
	v_fma_f32 v80, -v169, v46, v80
	v_fma_f32 v81, -v182, v4, v81
	v_fma_f32 v80, -v170, v47, v80
	v_fma_f32 v81, -v183, v5, v81
	v_fma_f32 v80, -v171, v48, v80
	v_fma_f32 v81, -v184, v6, v81
	v_fma_f32 v80, -v172, v49, v80
	v_fma_f32 v81, -v185, v7, v81
	v_fma_f32 v80, -v173, v50, v80
	v_fma_f32 v81, -v192, v8, v81
	v_fma_f32 v80, -v174, v51, v80
	v_fma_f32 v81, -v193, v9, v81
	v_fma_f32 v80, -v175, v78, v80
	v_fma_f32 v81, -v194, v10, v81
	v_fma_f32 v80, -v176, v79, v80
	v_fma_f32 v81, -v195, v12, v81
	ds_read_b128 v[100:103], v95 offset:61840
	ds_read_b128 v[104:107], v95 offset:61856
	ds_read_b128 v[108:111], v95 offset:61872
	ds_read_b128 v[112:115], v95 offset:62016
	ds_read_b128 v[116:119], v95 offset:62032
	ds_read_b128 v[162:165], v95 offset:62048
	ds_read_b128 v[166:169], v95 offset:62064
	ds_read_b128 v[170:173], v95 offset:62080
	ds_read_b128 v[174:177], v95 offset:62096
	ds_read_b128 v[178:181], v95 offset:62112
	ds_read_b128 v[182:185], v95 offset:62128
	ds_read_b128 v[190:193], v95 offset:62144
	s_waitcnt lgkmcnt(14)
	v_fma_f32 v82, -v142, v0, v82
	v_fma_f32 v82, -v143, v1, v82
	v_fma_f32 v81, -v120, v13, v81
	v_fma_f32 v82, -v144, v2, v82
	v_fma_f32 v81, -v121, v15, v81
	v_fma_f32 v82, -v145, v3, v82
	v_fma_f32 v81, -v122, v16, v81
	v_fma_f32 v82, -v146, v4, v82
	v_fma_f32 v81, -v123, v18, v81
	v_fma_f32 v82, -v147, v5, v82
	v_fma_f32 v81, -v124, v19, v81
	v_fma_f32 v82, -v148, v6, v82
	v_fma_f32 v81, -v125, v25, v81
	v_fma_f32 v82, -v149, v7, v82
	v_fma_f32 v81, -v126, v27, v81
	v_fma_f32 v82, -v150, v8, v82
	v_fma_f32 v81, -v127, v40, v81
	v_fma_f32 v82, -v151, v9, v82
	v_fma_f32 v81, -v128, v41, v81
	v_fma_f32 v82, -v152, v10, v82
	v_fma_f32 v81, -v129, v42, v81
	v_fma_f32 v82, -v153, v12, v82
	v_fma_f32 v81, -v130, v43, v81
	v_fma_f32 v82, -v154, v13, v82
	v_fma_f32 v81, -v131, v44, v81
	v_fma_f32 v82, -v155, v15, v82
	v_fma_f32 v81, -v132, v45, v81
	v_fma_f32 v82, -v156, v16, v82
	v_fma_f32 v81, -v133, v46, v81
	v_fma_f32 v82, -v157, v18, v82
	v_fma_f32 v81, -v134, v47, v81
	s_waitcnt lgkmcnt(13)
	v_fma_f32 v82, -v158, v19, v82
	v_fma_f32 v81, -v135, v48, v81
	v_fma_f32 v82, -v159, v25, v82
	v_fma_f32 v81, -v136, v49, v81
	v_fma_f32 v82, -v160, v27, v82
	v_fma_f32 v81, -v137, v50, v81
	v_fma_f32 v82, -v161, v40, v82
	v_fma_f32 v81, -v138, v51, v81
	s_waitcnt lgkmcnt(12)
	v_fma_f32 v82, -v186, v41, v82
	v_fma_f32 v81, -v139, v78, v81
	v_fma_f32 v82, -v187, v42, v82
	v_fma_f32 v81, -v140, v79, v81
	v_fma_f32 v82, -v188, v43, v82
	v_fma_f32 v81, -v141, v80, v81
	v_fma_f32 v82, -v189, v44, v82
	ds_read_b128 v[120:123], v95 offset:62288
	ds_read_b128 v[124:127], v95 offset:62304
	ds_read_b128 v[128:131], v95 offset:62320
	ds_read_b128 v[132:135], v95 offset:62336
	ds_read_b128 v[136:139], v95 offset:62352
	ds_read_b128 v[140:143], v95 offset:62368
	ds_read_b128 v[144:147], v95 offset:62384
	ds_read_b128 v[148:151], v95 offset:62400
	ds_read_b128 v[152:155], v95 offset:62416
	ds_read_b128 v[156:159], v95 offset:62432
	s_waitcnt lgkmcnt(0)
	ds_read_b128 v[158:161], v95 offset:62560
	ds_read_b128 v[186:189], v95 offset:62576
	v_fma_f32 v83, -v112, v0, v83
	v_fma_f32 v83, -v113, v1, v83
	v_fma_f32 v83, -v114, v2, v83
	v_fma_f32 v83, -v115, v3, v83
	v_fma_f32 v83, -v116, v4, v83
	v_fma_f32 v83, -v117, v5, v83
	v_fma_f32 v83, -v118, v6, v83
	v_fma_f32 v83, -v119, v7, v83
	v_fma_f32 v83, -v162, v8, v83
	v_fma_f32 v83, -v163, v9, v83
	v_fma_f32 v83, -v164, v10, v83
	v_fma_f32 v83, -v165, v12, v83
	v_fma_f32 v83, -v166, v13, v83
	v_fma_f32 v83, -v167, v15, v83
	v_fma_f32 v83, -v168, v16, v83
	v_fma_f32 v83, -v169, v18, v83
	v_fma_f32 v83, -v170, v19, v83
	v_fma_f32 v83, -v171, v25, v83
	v_fma_f32 v83, -v172, v27, v83
	v_fma_f32 v83, -v173, v40, v83
	v_fma_f32 v83, -v174, v41, v83
	v_fma_f32 v83, -v175, v42, v83
	v_fma_f32 v83, -v176, v43, v83
	v_fma_f32 v83, -v177, v44, v83
	v_fma_f32 v82, -v100, v45, v82
	v_fma_f32 v83, -v178, v45, v83
	v_fma_f32 v82, -v101, v46, v82
	v_fma_f32 v83, -v179, v46, v83
	v_fma_f32 v82, -v102, v47, v82
	v_fma_f32 v83, -v180, v47, v83
	v_fma_f32 v82, -v103, v48, v82
	v_fma_f32 v83, -v181, v48, v83
	v_fma_f32 v82, -v104, v49, v82
	v_fma_f32 v83, -v182, v49, v83
	v_fma_f32 v82, -v105, v50, v82
	v_fma_f32 v83, -v183, v50, v83
	v_fma_f32 v82, -v106, v51, v82
	v_fma_f32 v83, -v184, v51, v83
	v_fma_f32 v82, -v107, v78, v82
	v_fma_f32 v83, -v185, v78, v83
	v_fma_f32 v82, -v108, v79, v82
	v_fma_f32 v83, -v190, v79, v83
	v_fma_f32 v82, -v109, v80, v82
	v_fma_f32 v83, -v191, v80, v83
	v_fma_f32 v82, -v110, v81, v82
	v_fma_f32 v83, -v192, v81, v83
	v_fma_f32 v83, -v193, v82, v83
	ds_read_b128 v[100:103], v95 offset:62592
	ds_read_b128 v[104:107], v95 offset:62608
	ds_read_b128 v[108:111], v95 offset:62624
	ds_read_b128 v[112:115], v95 offset:62640
	ds_read_b128 v[116:119], v95 offset:62656
	ds_read_b128 v[162:165], v95 offset:62672
	ds_read_b128 v[166:169], v95 offset:62688
	ds_read_b128 v[170:173], v95 offset:62704
	s_waitcnt lgkmcnt(0)
	ds_read_b128 v[172:175], v95 offset:62832
	ds_read_b128 v[176:179], v95 offset:62848
	ds_read_b128 v[180:183], v95 offset:62864
	ds_read_b128 v[190:193], v95 offset:62880
	v_fma_f32 v85, -v120, v0, v85
	v_fma_f32 v85, -v121, v1, v85
	v_fma_f32 v85, -v122, v2, v85
	v_fma_f32 v85, -v123, v3, v85
	v_fma_f32 v85, -v124, v4, v85
	v_fma_f32 v85, -v125, v5, v85
	v_fma_f32 v85, -v126, v6, v85
	v_fma_f32 v85, -v127, v7, v85
	v_fma_f32 v85, -v128, v8, v85
	v_fma_f32 v85, -v129, v9, v85
	v_fma_f32 v85, -v130, v10, v85
	v_fma_f32 v85, -v131, v12, v85
	v_fma_f32 v85, -v132, v13, v85
	v_fma_f32 v85, -v133, v15, v85
	v_fma_f32 v85, -v134, v16, v85
	v_fma_f32 v85, -v135, v18, v85
	v_fma_f32 v85, -v136, v19, v85
	v_fma_f32 v85, -v137, v25, v85
	v_fma_f32 v85, -v138, v27, v85
	v_fma_f32 v85, -v139, v40, v85
	v_fma_f32 v85, -v140, v41, v85
	v_fma_f32 v85, -v141, v42, v85
	v_fma_f32 v85, -v142, v43, v85
	v_fma_f32 v85, -v143, v44, v85
	v_fma_f32 v85, -v144, v45, v85
	v_fma_f32 v85, -v145, v46, v85
	v_fma_f32 v85, -v146, v47, v85
	v_fma_f32 v85, -v147, v48, v85
	v_fma_f32 v85, -v148, v49, v85
	v_fma_f32 v85, -v149, v50, v85
	v_fma_f32 v87, -v158, v0, v87
	v_fma_f32 v85, -v150, v51, v85
	v_fma_f32 v87, -v159, v1, v87
	v_fma_f32 v85, -v151, v78, v85
	v_fma_f32 v87, -v160, v2, v87
	v_fma_f32 v85, -v152, v79, v85
	v_fma_f32 v87, -v161, v3, v87
	v_fma_f32 v85, -v153, v80, v85
	v_fma_f32 v87, -v186, v4, v87
	v_fma_f32 v85, -v154, v81, v85
	v_fma_f32 v87, -v187, v5, v87
	v_fma_f32 v85, -v155, v82, v85
	v_fma_f32 v87, -v188, v6, v87
	v_fma_f32 v85, -v156, v83, v85
	v_fma_f32 v87, -v189, v7, v87
	ds_read_b128 v[120:123], v95 offset:62896
	ds_read_b128 v[124:127], v95 offset:62912
	ds_read_b128 v[128:131], v95 offset:62928
	ds_read_b128 v[132:135], v95 offset:62944
	ds_read_b128 v[136:139], v95 offset:62960
	ds_read_b128 v[140:143], v95 offset:62976
	ds_read_b128 v[144:147], v95 offset:63104
	ds_read_b128 v[148:151], v95 offset:63120
	ds_read_b128 v[152:155], v95 offset:63136
	ds_read_b128 v[156:159], v95 offset:63152
	ds_read_b128 v[184:187], v95 offset:63168
	ds_read_b128 v[194:197], v95 offset:63184
	v_fma_f32 v87, -v100, v8, v87
	v_fma_f32 v87, -v101, v9, v87
	v_fma_f32 v87, -v102, v10, v87
	v_fma_f32 v87, -v103, v12, v87
	v_fma_f32 v87, -v104, v13, v87
	v_fma_f32 v87, -v105, v15, v87
	v_fma_f32 v87, -v106, v16, v87
	v_fma_f32 v87, -v107, v18, v87
	v_fma_f32 v87, -v108, v19, v87
	v_fma_f32 v87, -v109, v25, v87
	v_fma_f32 v87, -v110, v27, v87
	v_fma_f32 v87, -v111, v40, v87
	v_fma_f32 v87, -v112, v41, v87
	v_fma_f32 v87, -v113, v42, v87
	v_fma_f32 v87, -v114, v43, v87
	s_waitcnt lgkmcnt(14)
	v_fma_f32 v89, -v172, v0, v89
	v_fma_f32 v87, -v115, v44, v87
	v_fma_f32 v89, -v173, v1, v89
	v_fma_f32 v87, -v116, v45, v87
	v_fma_f32 v89, -v174, v2, v89
	v_fma_f32 v87, -v117, v46, v87
	v_fma_f32 v89, -v175, v3, v89
	v_fma_f32 v87, -v118, v47, v87
	v_fma_f32 v89, -v176, v4, v89
	v_fma_f32 v87, -v119, v48, v87
	v_fma_f32 v89, -v177, v5, v89
	v_fma_f32 v87, -v162, v49, v87
	v_fma_f32 v89, -v178, v6, v89
	v_fma_f32 v87, -v163, v50, v87
	v_fma_f32 v89, -v179, v7, v89
	v_fma_f32 v87, -v164, v51, v87
	s_waitcnt lgkmcnt(13)
	v_fma_f32 v89, -v180, v8, v89
	v_fma_f32 v87, -v165, v78, v87
	v_fma_f32 v89, -v181, v9, v89
	v_fma_f32 v87, -v166, v79, v87
	v_fma_f32 v89, -v182, v10, v89
	v_fma_f32 v87, -v167, v80, v87
	v_fma_f32 v89, -v183, v12, v89
	v_fma_f32 v87, -v168, v81, v87
	s_waitcnt lgkmcnt(12)
	v_fma_f32 v89, -v190, v13, v89
	v_fma_f32 v87, -v169, v82, v87
	v_fma_f32 v89, -v191, v15, v89
	v_fma_f32 v87, -v170, v83, v87
	v_fma_f32 v89, -v192, v16, v89
	v_fma_f32 v87, -v171, v85, v87
	v_fma_f32 v89, -v193, v18, v89
	ds_read_b128 v[100:103], v95 offset:63200
	ds_read_b128 v[104:107], v95 offset:63216
	ds_read_b128 v[108:111], v95 offset:63232
	ds_read_b128 v[112:115], v95 offset:63248
	ds_read_b128 v[116:119], v95 offset:63376
	ds_read_b128 v[160:163], v95 offset:63392
	ds_read_b128 v[164:167], v95 offset:63408
	ds_read_b128 v[168:171], v95 offset:63424
	ds_read_b128 v[172:175], v95 offset:63440
	ds_read_b128 v[176:179], v95 offset:63456
	ds_read_b128 v[180:183], v95 offset:63472
	ds_read_b128 v[188:191], v95 offset:63488
	s_waitcnt lgkmcnt(14)
	v_fma_f32 v91, -v144, v0, v91
	v_fma_f32 v89, -v120, v19, v89
	v_fma_f32 v91, -v145, v1, v91
	v_fma_f32 v89, -v121, v25, v89
	v_fma_f32 v91, -v146, v2, v91
	v_fma_f32 v89, -v122, v27, v89
	v_fma_f32 v91, -v147, v3, v91
	v_fma_f32 v89, -v123, v40, v89
	v_fma_f32 v91, -v148, v4, v91
	v_fma_f32 v89, -v124, v41, v89
	v_fma_f32 v91, -v149, v5, v91
	v_fma_f32 v89, -v125, v42, v89
	v_fma_f32 v91, -v150, v6, v91
	v_fma_f32 v89, -v126, v43, v89
	v_fma_f32 v91, -v151, v7, v91
	v_fma_f32 v89, -v127, v44, v89
	v_fma_f32 v91, -v152, v8, v91
	v_fma_f32 v89, -v128, v45, v89
	v_fma_f32 v91, -v153, v9, v91
	v_fma_f32 v89, -v129, v46, v89
	v_fma_f32 v91, -v154, v10, v91
	v_fma_f32 v89, -v130, v47, v89
	v_fma_f32 v91, -v155, v12, v91
	v_fma_f32 v89, -v131, v48, v89
	v_fma_f32 v91, -v156, v13, v91
	v_fma_f32 v89, -v132, v49, v89
	v_fma_f32 v91, -v157, v15, v91
	v_fma_f32 v89, -v133, v50, v89
	v_fma_f32 v91, -v158, v16, v91
	v_fma_f32 v89, -v134, v51, v89
	v_fma_f32 v91, -v159, v18, v91
	v_fma_f32 v89, -v135, v78, v89
	s_waitcnt lgkmcnt(13)
	v_fma_f32 v91, -v184, v19, v91
	v_fma_f32 v89, -v136, v79, v89
	v_fma_f32 v91, -v185, v25, v91
	v_fma_f32 v89, -v137, v80, v89
	v_fma_f32 v91, -v186, v27, v91
	v_fma_f32 v89, -v138, v81, v89
	v_fma_f32 v91, -v187, v40, v91
	v_fma_f32 v89, -v139, v82, v89
	s_waitcnt lgkmcnt(12)
	v_fma_f32 v91, -v194, v41, v91
	v_fma_f32 v89, -v140, v83, v89
	v_fma_f32 v91, -v195, v42, v91
	v_fma_f32 v89, -v141, v85, v89
	v_fma_f32 v91, -v196, v43, v91
	v_fma_f32 v89, -v142, v87, v89
	v_fma_f32 v91, -v197, v44, v91
	ds_read_b128 v[120:123], v95 offset:63504
	ds_read_b128 v[124:127], v95 offset:63520
	ds_read_b128 v[128:131], v95 offset:63536
	s_waitcnt lgkmcnt(0)
	ds_read_b128 v[130:133], v95 offset:63648
	ds_read_b128 v[134:137], v95 offset:63664
	ds_read_b128 v[138:141], v95 offset:63680
	ds_read_b128 v[142:145], v95 offset:63696
	ds_read_b128 v[146:149], v95 offset:63712
	ds_read_b128 v[150:153], v95 offset:63728
	ds_read_b128 v[154:157], v95 offset:63744
	ds_read_b128 v[184:187], v95 offset:63760
	ds_read_b128 v[192:195], v95 offset:63776
	v_fma_f32 v93, -v116, v0, v93
	v_fma_f32 v93, -v117, v1, v93
	v_fma_f32 v93, -v118, v2, v93
	v_fma_f32 v93, -v119, v3, v93
	v_fma_f32 v93, -v160, v4, v93
	v_fma_f32 v93, -v161, v5, v93
	v_fma_f32 v93, -v162, v6, v93
	v_fma_f32 v93, -v163, v7, v93
	v_fma_f32 v93, -v164, v8, v93
	v_fma_f32 v93, -v165, v9, v93
	v_fma_f32 v93, -v166, v10, v93
	v_fma_f32 v93, -v167, v12, v93
	v_fma_f32 v93, -v168, v13, v93
	v_fma_f32 v93, -v169, v15, v93
	v_fma_f32 v93, -v170, v16, v93
	v_fma_f32 v93, -v171, v18, v93
	v_fma_f32 v91, -v100, v45, v91
	v_fma_f32 v93, -v172, v19, v93
	v_fma_f32 v91, -v101, v46, v91
	v_fma_f32 v93, -v173, v25, v93
	v_fma_f32 v91, -v102, v47, v91
	v_fma_f32 v93, -v174, v27, v93
	v_fma_f32 v91, -v103, v48, v91
	v_fma_f32 v93, -v175, v40, v93
	v_fma_f32 v91, -v104, v49, v91
	v_fma_f32 v93, -v176, v41, v93
	v_fma_f32 v91, -v105, v50, v91
	v_fma_f32 v93, -v177, v42, v93
	v_fma_f32 v91, -v106, v51, v91
	v_fma_f32 v93, -v178, v43, v93
	v_fma_f32 v91, -v107, v78, v91
	v_fma_f32 v93, -v179, v44, v93
	v_fma_f32 v91, -v108, v79, v91
	v_fma_f32 v93, -v180, v45, v93
	v_fma_f32 v91, -v109, v80, v91
	v_fma_f32 v93, -v181, v46, v93
	v_fma_f32 v91, -v110, v81, v91
	v_fma_f32 v93, -v182, v47, v93
	v_fma_f32 v91, -v111, v82, v91
	v_fma_f32 v93, -v183, v48, v93
	v_fma_f32 v91, -v112, v83, v91
	v_fma_f32 v93, -v188, v49, v93
	v_fma_f32 v91, -v113, v85, v91
	v_fma_f32 v93, -v189, v50, v93
	v_fma_f32 v91, -v114, v87, v91
	v_fma_f32 v93, -v190, v51, v93
	v_fma_f32 v91, -v115, v89, v91
	v_fma_f32 v93, -v191, v78, v93
	ds_read_b128 v[100:103], v95 offset:63792
	ds_read_b128 v[104:107], v95 offset:63808
	s_waitcnt lgkmcnt(0)
	ds_read_b128 v[106:109], v95 offset:63920
	ds_read_b128 v[110:113], v95 offset:63936
	ds_read_b128 v[114:117], v95 offset:63952
	ds_read_b128 v[158:161], v95 offset:63968
	ds_read_b128 v[162:165], v95 offset:63984
	ds_read_b128 v[166:169], v95 offset:64000
	ds_read_b128 v[170:173], v95 offset:64016
	ds_read_b128 v[174:177], v95 offset:64032
	ds_read_b128 v[178:181], v95 offset:64048
	ds_read_b128 v[188:191], v95 offset:64064
	v_fma_f32 v96, -v130, v0, v96
	v_fma_f32 v96, -v131, v1, v96
	v_fma_f32 v96, -v132, v2, v96
	v_fma_f32 v96, -v133, v3, v96
	v_fma_f32 v96, -v134, v4, v96
	v_fma_f32 v96, -v135, v5, v96
	v_fma_f32 v96, -v136, v6, v96
	v_fma_f32 v96, -v137, v7, v96
	v_fma_f32 v96, -v138, v8, v96
	v_fma_f32 v96, -v139, v9, v96
	v_fma_f32 v96, -v140, v10, v96
	v_fma_f32 v96, -v141, v12, v96
	v_fma_f32 v96, -v142, v13, v96
	v_fma_f32 v96, -v143, v15, v96
	v_fma_f32 v96, -v144, v16, v96
	v_fma_f32 v96, -v145, v18, v96
	v_fma_f32 v96, -v146, v19, v96
	v_fma_f32 v96, -v147, v25, v96
	v_fma_f32 v96, -v148, v27, v96
	v_fma_f32 v96, -v149, v40, v96
	v_fma_f32 v96, -v150, v41, v96
	v_fma_f32 v96, -v151, v42, v96
	v_fma_f32 v96, -v152, v43, v96
	v_fma_f32 v96, -v153, v44, v96
	v_fma_f32 v96, -v154, v45, v96
	v_fma_f32 v96, -v155, v46, v96
	v_fma_f32 v96, -v156, v47, v96
	v_fma_f32 v93, -v120, v79, v93
	v_fma_f32 v96, -v157, v48, v96
	v_fma_f32 v93, -v121, v80, v93
	v_fma_f32 v96, -v184, v49, v96
	v_fma_f32 v93, -v122, v81, v93
	v_fma_f32 v96, -v185, v50, v96
	v_fma_f32 v93, -v123, v82, v93
	v_fma_f32 v96, -v186, v51, v96
	v_fma_f32 v93, -v124, v83, v93
	v_fma_f32 v96, -v187, v78, v96
	v_fma_f32 v93, -v125, v85, v93
	v_fma_f32 v96, -v192, v79, v96
	v_fma_f32 v93, -v126, v87, v93
	v_fma_f32 v96, -v193, v80, v96
	v_fma_f32 v93, -v127, v89, v93
	v_fma_f32 v96, -v194, v81, v96
	v_fma_f32 v93, -v128, v91, v93
	v_fma_f32 v96, -v195, v82, v96
	ds_read_b128 v[118:121], v95 offset:64080
	ds_read_b128 v[122:125], v95 offset:64192
	ds_read_b128 v[126:129], v95 offset:64208
	ds_read_b128 v[130:133], v95 offset:64224
	ds_read_b128 v[134:137], v95 offset:64240
	ds_read_b128 v[138:141], v95 offset:64256
	ds_read_b128 v[142:145], v95 offset:64272
	ds_read_b128 v[146:149], v95 offset:64288
	ds_read_b128 v[150:153], v95 offset:64304
	ds_read_b128 v[154:157], v95 offset:64320
	ds_read_b128 v[182:185], v95 offset:64336
	ds_read_b128 v[192:195], v95 offset:64352
	s_waitcnt lgkmcnt(14)
	v_fma_f32 v98, -v106, v0, v98
	v_fma_f32 v98, -v107, v1, v98
	v_fma_f32 v98, -v108, v2, v98
	v_fma_f32 v98, -v109, v3, v98
	v_fma_f32 v98, -v110, v4, v98
	v_fma_f32 v98, -v111, v5, v98
	v_fma_f32 v98, -v112, v6, v98
	v_fma_f32 v98, -v113, v7, v98
	v_fma_f32 v98, -v114, v8, v98
	v_fma_f32 v98, -v115, v9, v98
	v_fma_f32 v98, -v116, v10, v98
	v_fma_f32 v98, -v117, v12, v98
	v_fma_f32 v98, -v158, v13, v98
	v_fma_f32 v98, -v159, v15, v98
	v_fma_f32 v98, -v160, v16, v98
	v_fma_f32 v98, -v161, v18, v98
	v_fma_f32 v98, -v162, v19, v98
	v_fma_f32 v98, -v163, v25, v98
	v_fma_f32 v98, -v164, v27, v98
	v_fma_f32 v98, -v165, v40, v98
	v_fma_f32 v98, -v166, v41, v98
	v_fma_f32 v98, -v167, v42, v98
	v_fma_f32 v98, -v168, v43, v98
	v_fma_f32 v98, -v169, v44, v98
	v_fma_f32 v98, -v170, v45, v98
	v_fma_f32 v98, -v171, v46, v98
	v_fma_f32 v98, -v172, v47, v98
	v_fma_f32 v98, -v173, v48, v98
	v_fma_f32 v98, -v174, v49, v98
	v_fma_f32 v98, -v175, v50, v98
	v_fma_f32 v98, -v176, v51, v98
	v_fma_f32 v98, -v177, v78, v98
	s_waitcnt lgkmcnt(13)
	v_fma_f32 v98, -v178, v79, v98
	v_fma_f32 v98, -v179, v80, v98
	v_fma_f32 v96, -v100, v83, v96
	v_fma_f32 v98, -v180, v81, v98
	v_fma_f32 v96, -v101, v85, v96
	v_fma_f32 v98, -v181, v82, v98
	v_fma_f32 v96, -v102, v87, v96
	s_waitcnt lgkmcnt(12)
	v_fma_f32 v98, -v188, v83, v98
	v_fma_f32 v96, -v103, v89, v96
	v_fma_f32 v98, -v189, v85, v98
	v_fma_f32 v96, -v104, v91, v96
	v_fma_f32 v98, -v190, v87, v98
	v_fma_f32 v96, -v105, v93, v96
	v_fma_f32 v98, -v191, v89, v98
	ds_read_b128 v[100:103], v95 offset:64464
	ds_read_b128 v[104:107], v95 offset:64480
	ds_read_b128 v[108:111], v95 offset:64496
	ds_read_b128 v[112:115], v95 offset:64512
	ds_read_b128 v[158:161], v95 offset:64528
	ds_read_b128 v[162:165], v95 offset:64544
	ds_read_b128 v[166:169], v95 offset:64560
	ds_read_b128 v[170:173], v95 offset:64576
	ds_read_b128 v[174:177], v95 offset:64592
	ds_read_b128 v[178:181], v95 offset:64608
	ds_read_b128 v[186:189], v95 offset:64624
	ds_read_b128 v[196:199], v95 offset:64640
	s_waitcnt lgkmcnt(14)
	v_fma_f32 v99, -v122, v0, v99
	v_fma_f32 v99, -v123, v1, v99
	v_fma_f32 v99, -v124, v2, v99
	v_fma_f32 v99, -v125, v3, v99
	v_fma_f32 v99, -v126, v4, v99
	v_fma_f32 v99, -v127, v5, v99
	v_fma_f32 v99, -v128, v6, v99
	v_fma_f32 v99, -v129, v7, v99
	v_fma_f32 v99, -v130, v8, v99
	v_fma_f32 v99, -v131, v9, v99
	v_fma_f32 v99, -v132, v10, v99
	v_fma_f32 v99, -v133, v12, v99
	v_fma_f32 v99, -v134, v13, v99
	v_fma_f32 v99, -v135, v15, v99
	v_fma_f32 v99, -v136, v16, v99
	v_fma_f32 v99, -v137, v18, v99
	v_fma_f32 v99, -v138, v19, v99
	v_fma_f32 v99, -v139, v25, v99
	v_fma_f32 v99, -v140, v27, v99
	v_fma_f32 v99, -v141, v40, v99
	v_fma_f32 v99, -v142, v41, v99
	v_fma_f32 v99, -v143, v42, v99
	v_fma_f32 v99, -v144, v43, v99
	v_fma_f32 v99, -v145, v44, v99
	v_fma_f32 v99, -v146, v45, v99
	v_fma_f32 v99, -v147, v46, v99
	v_fma_f32 v99, -v148, v47, v99
	v_fma_f32 v99, -v149, v48, v99
	v_fma_f32 v99, -v150, v49, v99
	v_fma_f32 v99, -v151, v50, v99
	v_fma_f32 v99, -v152, v51, v99
	v_fma_f32 v99, -v153, v78, v99
	v_fma_f32 v99, -v154, v79, v99
	v_fma_f32 v99, -v155, v80, v99
	v_fma_f32 v99, -v156, v81, v99
	v_fma_f32 v99, -v157, v82, v99
	s_waitcnt lgkmcnt(13)
	v_fma_f32 v99, -v182, v83, v99
	v_fma_f32 v99, -v183, v85, v99
	v_fma_f32 v99, -v184, v87, v99
	v_fma_f32 v99, -v185, v89, v99
	v_fma_f32 v98, -v118, v91, v98
	s_waitcnt lgkmcnt(12)
	v_fma_f32 v99, -v192, v91, v99
	v_fma_f32 v98, -v119, v93, v98
	v_fma_f32 v99, -v193, v93, v99
	v_fma_f32 v98, -v120, v96, v98
	v_fma_f32 v99, -v194, v96, v99
	v_fma_f32 v99, -v195, v98, v99
	ds_read_b128 v[116:119], v95 offset:64736
	ds_read_b128 v[120:123], v95 offset:64752
	ds_read_b128 v[124:127], v95 offset:64768
	ds_read_b128 v[128:131], v95 offset:64784
	ds_read_b128 v[132:135], v95 offset:64800
	ds_read_b128 v[136:139], v95 offset:64816
	ds_read_b128 v[140:143], v95 offset:64832
	ds_read_b128 v[144:147], v95 offset:64848
	ds_read_b128 v[148:151], v95 offset:64864
	ds_read_b128 v[152:155], v95 offset:64880
	ds_read_b128 v[182:185], v95 offset:64896
	ds_read_b128 v[190:193], v95 offset:64912
	s_waitcnt lgkmcnt(14)
	v_fma_f32 v97, -v100, v0, v97
	v_fma_f32 v97, -v101, v1, v97
	v_fma_f32 v97, -v102, v2, v97
	v_fma_f32 v97, -v103, v3, v97
	v_fma_f32 v97, -v104, v4, v97
	v_fma_f32 v97, -v105, v5, v97
	v_fma_f32 v97, -v106, v6, v97
	v_fma_f32 v97, -v107, v7, v97
	v_fma_f32 v97, -v108, v8, v97
	v_fma_f32 v97, -v109, v9, v97
	v_fma_f32 v97, -v110, v10, v97
	v_fma_f32 v97, -v111, v12, v97
	v_fma_f32 v97, -v112, v13, v97
	v_fma_f32 v97, -v113, v15, v97
	v_fma_f32 v97, -v114, v16, v97
	v_fma_f32 v97, -v115, v18, v97
	v_fma_f32 v97, -v158, v19, v97
	v_fma_f32 v97, -v159, v25, v97
	v_fma_f32 v97, -v160, v27, v97
	v_fma_f32 v97, -v161, v40, v97
	v_fma_f32 v97, -v162, v41, v97
	v_fma_f32 v97, -v163, v42, v97
	v_fma_f32 v97, -v164, v43, v97
	v_fma_f32 v97, -v165, v44, v97
	v_fma_f32 v97, -v166, v45, v97
	v_fma_f32 v97, -v167, v46, v97
	v_fma_f32 v97, -v168, v47, v97
	v_fma_f32 v97, -v169, v48, v97
	v_fma_f32 v97, -v170, v49, v97
	v_fma_f32 v97, -v171, v50, v97
	v_fma_f32 v97, -v172, v51, v97
	v_fma_f32 v97, -v173, v78, v97
	v_fma_f32 v97, -v174, v79, v97
	v_fma_f32 v97, -v175, v80, v97
	v_fma_f32 v97, -v176, v81, v97
	v_fma_f32 v97, -v177, v82, v97
	v_fma_f32 v97, -v178, v83, v97
	v_fma_f32 v97, -v179, v85, v97
	v_fma_f32 v97, -v180, v87, v97
	v_fma_f32 v97, -v181, v89, v97
	s_waitcnt lgkmcnt(13)
	v_fma_f32 v97, -v186, v91, v97
	v_fma_f32 v97, -v187, v93, v97
	v_fma_f32 v97, -v188, v96, v97
	v_fma_f32 v97, -v189, v98, v97
	s_waitcnt lgkmcnt(12)
	v_fma_f32 v97, -v196, v99, v97
	ds_read_b128 v[100:103], v95 offset:65008
	ds_read_b128 v[104:107], v95 offset:65024
	ds_read_b128 v[108:111], v95 offset:65040
	ds_read_b128 v[112:115], v95 offset:65056
	ds_read_b128 v[156:159], v95 offset:65072
	ds_read_b128 v[160:163], v95 offset:65088
	ds_read_b128 v[164:167], v95 offset:65104
	ds_read_b128 v[168:171], v95 offset:65120
	ds_read_b128 v[172:175], v95 offset:65136
	ds_read_b128 v[176:179], v95 offset:65152
	ds_read_b128 v[186:189], v95 offset:65168
	s_waitcnt lgkmcnt(11)
	ds_read_b128 v[192:195], v95 offset:65184
	v_fma_f32 v94, -v116, v0, v94
	v_fma_f32 v94, -v117, v1, v94
	v_fma_f32 v94, -v118, v2, v94
	v_fma_f32 v94, -v119, v3, v94
	v_fma_f32 v94, -v120, v4, v94
	v_fma_f32 v94, -v121, v5, v94
	v_fma_f32 v94, -v122, v6, v94
	v_fma_f32 v94, -v123, v7, v94
	v_fma_f32 v94, -v124, v8, v94
	v_fma_f32 v94, -v125, v9, v94
	v_fma_f32 v94, -v126, v10, v94
	v_fma_f32 v94, -v127, v12, v94
	v_fma_f32 v94, -v128, v13, v94
	v_fma_f32 v94, -v129, v15, v94
	v_fma_f32 v94, -v130, v16, v94
	v_fma_f32 v94, -v131, v18, v94
	v_fma_f32 v94, -v132, v19, v94
	v_fma_f32 v94, -v133, v25, v94
	v_fma_f32 v94, -v134, v27, v94
	v_fma_f32 v94, -v135, v40, v94
	v_fma_f32 v94, -v136, v41, v94
	v_fma_f32 v94, -v137, v42, v94
	v_fma_f32 v94, -v138, v43, v94
	v_fma_f32 v94, -v139, v44, v94
	v_fma_f32 v94, -v140, v45, v94
	v_fma_f32 v94, -v141, v46, v94
	v_fma_f32 v94, -v142, v47, v94
	v_fma_f32 v94, -v143, v48, v94
	v_fma_f32 v94, -v144, v49, v94
	v_fma_f32 v94, -v145, v50, v94
	v_fma_f32 v94, -v146, v51, v94
	v_fma_f32 v94, -v147, v78, v94
	v_fma_f32 v94, -v148, v79, v94
	v_fma_f32 v94, -v149, v80, v94
	v_fma_f32 v94, -v150, v81, v94
	v_fma_f32 v94, -v151, v82, v94
	v_fma_f32 v94, -v152, v83, v94
	v_fma_f32 v94, -v153, v85, v94
	v_fma_f32 v94, -v154, v87, v94
	v_fma_f32 v94, -v155, v89, v94
	v_fma_f32 v94, -v182, v91, v94
	v_fma_f32 v94, -v183, v93, v94
	v_fma_f32 v94, -v184, v96, v94
	v_fma_f32 v94, -v185, v98, v94
	v_fma_f32 v94, -v190, v99, v94
	v_fma_f32 v94, -v191, v97, v94
	ds_read_b128 v[116:119], v95 offset:65280
	ds_read_b128 v[120:123], v95 offset:65296
	ds_read_b128 v[124:127], v95 offset:65312
	ds_read_b128 v[128:131], v95 offset:65328
	ds_read_b128 v[132:135], v95 offset:65344
	ds_read_b128 v[136:139], v95 offset:65360
	ds_read_b128 v[140:143], v95 offset:65376
	ds_read_b128 v[144:147], v95 offset:65392
	ds_read_b128 v[148:151], v95 offset:65408
	ds_read_b128 v[152:155], v95 offset:65424
	ds_read_b128 v[180:183], v95 offset:65440
	ds_read_b128 v[196:199], v95 offset:65456
	s_waitcnt lgkmcnt(14)
	v_fma_f32 v92, -v100, v0, v92
	v_fma_f32 v92, -v101, v1, v92
	v_fma_f32 v92, -v102, v2, v92
	v_fma_f32 v92, -v103, v3, v92
	v_fma_f32 v92, -v104, v4, v92
	v_fma_f32 v92, -v105, v5, v92
	v_fma_f32 v92, -v106, v6, v92
	v_fma_f32 v92, -v107, v7, v92
	v_fma_f32 v92, -v108, v8, v92
	v_fma_f32 v92, -v109, v9, v92
	v_fma_f32 v92, -v110, v10, v92
	v_fma_f32 v92, -v111, v12, v92
	v_fma_f32 v92, -v112, v13, v92
	v_fma_f32 v92, -v113, v15, v92
	v_fma_f32 v92, -v114, v16, v92
	v_fma_f32 v92, -v115, v18, v92
	v_fma_f32 v92, -v156, v19, v92
	v_fma_f32 v92, -v157, v25, v92
	v_fma_f32 v92, -v158, v27, v92
	v_fma_f32 v92, -v159, v40, v92
	v_fma_f32 v92, -v160, v41, v92
	v_fma_f32 v92, -v161, v42, v92
	v_fma_f32 v92, -v162, v43, v92
	v_fma_f32 v92, -v163, v44, v92
	v_fma_f32 v92, -v164, v45, v92
	v_fma_f32 v92, -v165, v46, v92
	v_fma_f32 v92, -v166, v47, v92
	v_fma_f32 v92, -v167, v48, v92
	v_fma_f32 v92, -v168, v49, v92
	v_fma_f32 v92, -v169, v50, v92
	v_fma_f32 v92, -v170, v51, v92
	v_fma_f32 v92, -v171, v78, v92
	v_fma_f32 v92, -v172, v79, v92
	v_fma_f32 v92, -v173, v80, v92
	v_fma_f32 v92, -v174, v81, v92
	v_fma_f32 v92, -v175, v82, v92
	v_fma_f32 v92, -v176, v83, v92
	v_fma_f32 v92, -v177, v85, v92
	v_fma_f32 v92, -v178, v87, v92
	v_fma_f32 v92, -v179, v89, v92
	s_waitcnt lgkmcnt(13)
	v_fma_f32 v92, -v186, v91, v92
	v_fma_f32 v92, -v187, v93, v92
	v_fma_f32 v92, -v188, v96, v92
	v_fma_f32 v92, -v189, v98, v92
	s_waitcnt lgkmcnt(12)
	v_fma_f32 v92, -v192, v99, v92
	v_fma_f32 v92, -v193, v97, v92
	v_fma_f32 v92, -v194, v94, v92
	ds_read_b128 v[100:103], v14 offset:13328
	ds_read_b128 v[104:107], v14 offset:13344
	ds_read_b128 v[108:111], v14 offset:13360
	ds_read_b128 v[112:115], v14 offset:13376
	ds_read_b128 v[156:159], v14 offset:13392
	ds_read_b128 v[160:163], v14 offset:13408
	ds_read_b128 v[164:167], v14 offset:13424
	ds_read_b128 v[168:171], v14 offset:13440
	ds_read_b128 v[172:175], v14 offset:13456
	ds_read_b128 v[176:179], v14 offset:13472
	ds_read_b128 v[184:187], v14 offset:13488
	ds_read_b128 v[188:191], v14 offset:13504
	s_waitcnt lgkmcnt(14)
	v_fma_f32 v90, -v116, v0, v90
	v_fma_f32 v90, -v117, v1, v90
	v_fma_f32 v90, -v118, v2, v90
	v_fma_f32 v90, -v119, v3, v90
	v_fma_f32 v90, -v120, v4, v90
	v_fma_f32 v90, -v121, v5, v90
	v_fma_f32 v90, -v122, v6, v90
	v_fma_f32 v90, -v123, v7, v90
	v_fma_f32 v90, -v124, v8, v90
	v_fma_f32 v90, -v125, v9, v90
	v_fma_f32 v90, -v126, v10, v90
	v_fma_f32 v90, -v127, v12, v90
	v_fma_f32 v90, -v128, v13, v90
	v_fma_f32 v90, -v129, v15, v90
	v_fma_f32 v90, -v130, v16, v90
	v_fma_f32 v90, -v131, v18, v90
	v_fma_f32 v90, -v132, v19, v90
	v_fma_f32 v90, -v133, v25, v90
	v_fma_f32 v90, -v134, v27, v90
	v_fma_f32 v90, -v135, v40, v90
	v_fma_f32 v90, -v136, v41, v90
	v_fma_f32 v90, -v137, v42, v90
	v_fma_f32 v90, -v138, v43, v90
	v_fma_f32 v90, -v139, v44, v90
	v_fma_f32 v90, -v140, v45, v90
	v_fma_f32 v90, -v141, v46, v90
	v_fma_f32 v90, -v142, v47, v90
	v_fma_f32 v90, -v143, v48, v90
	v_fma_f32 v90, -v144, v49, v90
	v_fma_f32 v90, -v145, v50, v90
	v_fma_f32 v90, -v146, v51, v90
	v_fma_f32 v90, -v147, v78, v90
	v_fma_f32 v90, -v148, v79, v90
	v_fma_f32 v90, -v149, v80, v90
	v_fma_f32 v90, -v150, v81, v90
	v_fma_f32 v90, -v151, v82, v90
	v_fma_f32 v90, -v152, v83, v90
	v_fma_f32 v90, -v153, v85, v90
	v_fma_f32 v90, -v154, v87, v90
	v_fma_f32 v90, -v155, v89, v90
	s_waitcnt lgkmcnt(13)
	v_fma_f32 v90, -v180, v91, v90
	v_fma_f32 v90, -v181, v93, v90
	v_fma_f32 v90, -v182, v96, v90
	v_fma_f32 v90, -v183, v98, v90
	s_waitcnt lgkmcnt(12)
	v_fma_f32 v90, -v196, v99, v90
	v_fma_f32 v90, -v197, v97, v90
	v_fma_f32 v90, -v198, v94, v90
	v_fma_f32 v90, -v199, v92, v90
	ds_read_b128 v[116:119], v14 offset:13520
	s_waitcnt lgkmcnt(0)
	ds_read_b128 v[118:121], v14 offset:13600
	ds_read_b128 v[122:125], v14 offset:13616
	ds_read_b128 v[126:129], v14 offset:13632
	ds_read_b128 v[130:133], v14 offset:13648
	ds_read_b128 v[134:137], v14 offset:13664
	ds_read_b128 v[138:141], v14 offset:13680
	ds_read_b128 v[142:145], v14 offset:13696
	ds_read_b128 v[146:149], v14 offset:13712
	ds_read_b128 v[150:153], v14 offset:13728
	ds_read_b128 v[180:183], v14 offset:13744
	ds_read_b128 v[192:195], v14 offset:13760
	v_fma_f32 v88, -v100, v0, v88
	v_fma_f32 v88, -v101, v1, v88
	v_fma_f32 v88, -v102, v2, v88
	v_fma_f32 v88, -v103, v3, v88
	v_fma_f32 v88, -v104, v4, v88
	v_fma_f32 v88, -v105, v5, v88
	v_fma_f32 v88, -v106, v6, v88
	v_fma_f32 v88, -v107, v7, v88
	v_fma_f32 v88, -v108, v8, v88
	v_fma_f32 v88, -v109, v9, v88
	v_fma_f32 v88, -v110, v10, v88
	v_fma_f32 v88, -v111, v12, v88
	v_fma_f32 v88, -v112, v13, v88
	v_fma_f32 v88, -v113, v15, v88
	v_fma_f32 v88, -v114, v16, v88
	v_fma_f32 v88, -v115, v18, v88
	v_fma_f32 v88, -v156, v19, v88
	v_fma_f32 v88, -v157, v25, v88
	v_fma_f32 v88, -v158, v27, v88
	v_fma_f32 v88, -v159, v40, v88
	v_fma_f32 v88, -v160, v41, v88
	v_fma_f32 v88, -v161, v42, v88
	v_fma_f32 v88, -v162, v43, v88
	v_fma_f32 v88, -v163, v44, v88
	v_fma_f32 v88, -v164, v45, v88
	v_fma_f32 v88, -v165, v46, v88
	v_fma_f32 v88, -v166, v47, v88
	v_fma_f32 v88, -v167, v48, v88
	v_fma_f32 v88, -v168, v49, v88
	v_fma_f32 v88, -v169, v50, v88
	v_fma_f32 v88, -v170, v51, v88
	v_fma_f32 v88, -v171, v78, v88
	v_fma_f32 v88, -v172, v79, v88
	v_fma_f32 v88, -v173, v80, v88
	v_fma_f32 v88, -v174, v81, v88
	v_fma_f32 v88, -v175, v82, v88
	v_fma_f32 v88, -v176, v83, v88
	v_fma_f32 v88, -v177, v85, v88
	v_fma_f32 v88, -v178, v87, v88
	v_fma_f32 v88, -v179, v89, v88
	v_fma_f32 v88, -v184, v91, v88
	v_fma_f32 v88, -v185, v93, v88
	v_fma_f32 v88, -v186, v96, v88
	v_fma_f32 v88, -v187, v98, v88
	v_fma_f32 v88, -v188, v99, v88
	v_fma_f32 v88, -v189, v97, v88
	v_fma_f32 v88, -v190, v94, v88
	v_fma_f32 v88, -v191, v92, v88
	ds_read_b128 v[100:103], v14 offset:13776
	ds_read_b128 v[104:107], v14 offset:13792
	s_waitcnt lgkmcnt(0)
	ds_read_b128 v[106:109], v14 offset:13872
	ds_read_b128 v[110:113], v14 offset:13888
	ds_read_b128 v[154:157], v14 offset:13904
	ds_read_b128 v[158:161], v14 offset:13920
	ds_read_b128 v[162:165], v14 offset:13936
	ds_read_b128 v[166:169], v14 offset:13952
	ds_read_b128 v[170:173], v14 offset:13968
	ds_read_b128 v[174:177], v14 offset:13984
	ds_read_b128 v[184:187], v14 offset:14000
	ds_read_b128 v[188:191], v14 offset:14016
	v_fma_f32 v86, -v118, v0, v86
	v_fma_f32 v86, -v119, v1, v86
	v_fma_f32 v86, -v120, v2, v86
	v_fma_f32 v86, -v121, v3, v86
	v_fma_f32 v86, -v122, v4, v86
	v_fma_f32 v86, -v123, v5, v86
	v_fma_f32 v86, -v124, v6, v86
	v_fma_f32 v86, -v125, v7, v86
	v_fma_f32 v86, -v126, v8, v86
	v_fma_f32 v86, -v127, v9, v86
	v_fma_f32 v86, -v128, v10, v86
	v_fma_f32 v86, -v129, v12, v86
	v_fma_f32 v86, -v130, v13, v86
	v_fma_f32 v86, -v131, v15, v86
	v_fma_f32 v86, -v132, v16, v86
	v_fma_f32 v86, -v133, v18, v86
	v_fma_f32 v86, -v134, v19, v86
	v_fma_f32 v86, -v135, v25, v86
	v_fma_f32 v86, -v136, v27, v86
	v_fma_f32 v86, -v137, v40, v86
	v_fma_f32 v86, -v138, v41, v86
	v_fma_f32 v86, -v139, v42, v86
	v_fma_f32 v86, -v140, v43, v86
	v_fma_f32 v86, -v141, v44, v86
	v_fma_f32 v86, -v142, v45, v86
	v_fma_f32 v86, -v143, v46, v86
	v_fma_f32 v86, -v144, v47, v86
	v_fma_f32 v86, -v145, v48, v86
	v_fma_f32 v86, -v146, v49, v86
	v_fma_f32 v86, -v147, v50, v86
	v_fma_f32 v86, -v148, v51, v86
	v_fma_f32 v86, -v149, v78, v86
	v_fma_f32 v86, -v150, v79, v86
	v_fma_f32 v86, -v151, v80, v86
	v_fma_f32 v86, -v152, v81, v86
	v_fma_f32 v86, -v153, v82, v86
	v_fma_f32 v86, -v180, v83, v86
	v_fma_f32 v86, -v181, v85, v86
	v_fma_f32 v86, -v182, v87, v86
	v_fma_f32 v86, -v183, v89, v86
	v_fma_f32 v86, -v192, v91, v86
	v_fma_f32 v86, -v193, v93, v86
	v_fma_f32 v86, -v194, v96, v86
	v_fma_f32 v88, -v116, v90, v88
	v_fma_f32 v86, -v195, v98, v86
	ds_read_b128 v[114:117], v14 offset:14032
	ds_read_b128 v[118:121], v14 offset:14048
	ds_read_b128 v[122:125], v14 offset:14064
	ds_read_b128 v[126:129], v14 offset:14144
	ds_read_b128 v[130:133], v14 offset:14160
	ds_read_b128 v[134:137], v14 offset:14176
	ds_read_b128 v[138:141], v14 offset:14192
	ds_read_b128 v[142:145], v14 offset:14208
	ds_read_b128 v[146:149], v14 offset:14224
	ds_read_b128 v[150:153], v14 offset:14240
	ds_read_b128 v[178:181], v14 offset:14256
	ds_read_b128 v[192:195], v14 offset:14272
	s_waitcnt lgkmcnt(14)
	v_fma_f32 v84, -v106, v0, v84
	v_fma_f32 v84, -v107, v1, v84
	v_fma_f32 v84, -v108, v2, v84
	v_fma_f32 v84, -v109, v3, v84
	v_fma_f32 v84, -v110, v4, v84
	v_fma_f32 v84, -v111, v5, v84
	v_fma_f32 v84, -v112, v6, v84
	v_fma_f32 v84, -v113, v7, v84
	v_fma_f32 v84, -v154, v8, v84
	v_fma_f32 v84, -v155, v9, v84
	v_fma_f32 v84, -v156, v10, v84
	v_fma_f32 v84, -v157, v12, v84
	v_fma_f32 v84, -v158, v13, v84
	v_fma_f32 v84, -v159, v15, v84
	v_fma_f32 v84, -v160, v16, v84
	v_fma_f32 v84, -v161, v18, v84
	v_fma_f32 v84, -v162, v19, v84
	v_fma_f32 v84, -v163, v25, v84
	v_fma_f32 v84, -v164, v27, v84
	v_fma_f32 v84, -v165, v40, v84
	v_fma_f32 v84, -v166, v41, v84
	v_fma_f32 v84, -v167, v42, v84
	v_fma_f32 v84, -v168, v43, v84
	v_fma_f32 v84, -v169, v44, v84
	v_fma_f32 v84, -v170, v45, v84
	v_fma_f32 v84, -v171, v46, v84
	v_fma_f32 v84, -v172, v47, v84
	v_fma_f32 v84, -v173, v48, v84
	v_fma_f32 v84, -v174, v49, v84
	v_fma_f32 v84, -v175, v50, v84
	v_fma_f32 v84, -v176, v51, v84
	v_fma_f32 v84, -v177, v78, v84
	s_waitcnt lgkmcnt(13)
	v_fma_f32 v84, -v184, v79, v84
	v_fma_f32 v84, -v185, v80, v84
	v_fma_f32 v86, -v100, v99, v86
	v_fma_f32 v84, -v186, v81, v84
	v_fma_f32 v86, -v101, v97, v86
	v_fma_f32 v84, -v187, v82, v84
	v_fma_f32 v86, -v102, v94, v86
	s_waitcnt lgkmcnt(12)
	v_fma_f32 v84, -v188, v83, v84
	v_fma_f32 v86, -v103, v92, v86
	v_fma_f32 v84, -v189, v85, v84
	v_fma_f32 v86, -v104, v90, v86
	v_fma_f32 v84, -v190, v87, v84
	v_fma_f32 v86, -v105, v88, v86
	v_fma_f32 v84, -v191, v89, v84
	ds_read_b128 v[100:103], v14 offset:14288
	ds_read_b128 v[104:107], v14 offset:14304
	ds_read_b128 v[108:111], v14 offset:14320
	ds_read_b128 v[154:157], v14 offset:14336
	ds_read_b128 v[158:161], v14 offset:14416
	ds_read_b128 v[162:165], v14 offset:14432
	ds_read_b128 v[166:169], v14 offset:14448
	ds_read_b128 v[170:173], v14 offset:14464
	ds_read_b128 v[174:177], v14 offset:14480
	ds_read_b128 v[182:185], v14 offset:14496
	ds_read_b128 v[186:189], v14 offset:14512
	ds_read_b128 v[196:199], v14 offset:14528
	s_waitcnt lgkmcnt(14)
	v_fma_f32 v35, -v126, v0, v35
	v_fma_f32 v35, -v127, v1, v35
	v_fma_f32 v35, -v128, v2, v35
	v_fma_f32 v35, -v129, v3, v35
	v_fma_f32 v35, -v130, v4, v35
	v_fma_f32 v35, -v131, v5, v35
	v_fma_f32 v35, -v132, v6, v35
	v_fma_f32 v35, -v133, v7, v35
	v_fma_f32 v35, -v134, v8, v35
	v_fma_f32 v35, -v135, v9, v35
	v_fma_f32 v35, -v136, v10, v35
	v_fma_f32 v35, -v137, v12, v35
	v_fma_f32 v35, -v138, v13, v35
	v_fma_f32 v35, -v139, v15, v35
	v_fma_f32 v35, -v140, v16, v35
	v_fma_f32 v35, -v141, v18, v35
	v_fma_f32 v35, -v142, v19, v35
	v_fma_f32 v35, -v143, v25, v35
	v_fma_f32 v35, -v144, v27, v35
	v_fma_f32 v35, -v145, v40, v35
	v_fma_f32 v35, -v146, v41, v35
	v_fma_f32 v35, -v147, v42, v35
	v_fma_f32 v35, -v148, v43, v35
	v_fma_f32 v35, -v149, v44, v35
	v_fma_f32 v35, -v150, v45, v35
	v_fma_f32 v35, -v151, v46, v35
	v_fma_f32 v84, -v114, v91, v84
	v_fma_f32 v35, -v152, v47, v35
	v_fma_f32 v84, -v115, v93, v84
	v_fma_f32 v35, -v153, v48, v35
	v_fma_f32 v84, -v116, v96, v84
	s_waitcnt lgkmcnt(13)
	v_fma_f32 v35, -v178, v49, v35
	v_fma_f32 v84, -v117, v98, v84
	v_fma_f32 v35, -v179, v50, v35
	v_fma_f32 v84, -v118, v99, v84
	v_fma_f32 v35, -v180, v51, v35
	v_fma_f32 v84, -v119, v97, v84
	v_fma_f32 v35, -v181, v78, v35
	v_fma_f32 v84, -v120, v94, v84
	s_waitcnt lgkmcnt(12)
	v_fma_f32 v35, -v192, v79, v35
	v_fma_f32 v84, -v121, v92, v84
	v_fma_f32 v35, -v193, v80, v35
	v_fma_f32 v84, -v122, v90, v84
	v_fma_f32 v35, -v194, v81, v35
	v_fma_f32 v84, -v123, v88, v84
	v_fma_f32 v35, -v195, v82, v35
	v_fma_f32 v84, -v124, v86, v84
	s_barrier
	ds_read_b128 v[112:115], v14 offset:14544
	ds_read_b128 v[116:119], v14 offset:14560
	ds_read_b128 v[120:123], v14 offset:14576
	ds_read_b128 v[124:127], v14 offset:14592
	ds_read_b128 v[128:131], v14 offset:14608
	ds_read_b128 v[132:135], v14 offset:14624
	s_waitcnt lgkmcnt(0)
	ds_read_b128 v[134:137], v14 offset:14688
	ds_read_b128 v[138:141], v14 offset:14704
	ds_read_b128 v[142:145], v14 offset:14720
	ds_read_b128 v[146:149], v14 offset:14736
	ds_read_b128 v[150:153], v14 offset:14752
	ds_read_b128 v[178:181], v14 offset:14768
	v_fma_f32 v34, -v158, v0, v34
	v_fma_f32 v34, -v159, v1, v34
	v_fma_f32 v34, -v160, v2, v34
	v_fma_f32 v34, -v161, v3, v34
	v_fma_f32 v34, -v162, v4, v34
	v_fma_f32 v34, -v163, v5, v34
	v_fma_f32 v34, -v164, v6, v34
	v_fma_f32 v34, -v165, v7, v34
	v_fma_f32 v34, -v166, v8, v34
	v_fma_f32 v34, -v167, v9, v34
	v_fma_f32 v34, -v168, v10, v34
	v_fma_f32 v34, -v169, v12, v34
	v_fma_f32 v34, -v170, v13, v34
	v_fma_f32 v34, -v171, v15, v34
	v_fma_f32 v34, -v172, v16, v34
	v_fma_f32 v34, -v173, v18, v34
	v_fma_f32 v34, -v174, v19, v34
	v_fma_f32 v35, -v100, v83, v35
	v_fma_f32 v34, -v175, v25, v34
	v_fma_f32 v35, -v101, v85, v35
	v_fma_f32 v34, -v176, v27, v34
	v_fma_f32 v35, -v102, v87, v35
	v_fma_f32 v34, -v177, v40, v34
	v_fma_f32 v35, -v103, v89, v35
	v_fma_f32 v34, -v182, v41, v34
	v_fma_f32 v35, -v104, v91, v35
	v_fma_f32 v34, -v183, v42, v34
	v_fma_f32 v35, -v105, v93, v35
	v_fma_f32 v34, -v184, v43, v34
	v_fma_f32 v35, -v106, v96, v35
	v_fma_f32 v34, -v185, v44, v34
	v_fma_f32 v35, -v107, v98, v35
	v_fma_f32 v34, -v186, v45, v34
	v_fma_f32 v35, -v108, v99, v35
	v_fma_f32 v34, -v187, v46, v34
	v_fma_f32 v35, -v109, v97, v35
	v_fma_f32 v34, -v188, v47, v34
	v_fma_f32 v35, -v110, v94, v35
	v_fma_f32 v34, -v189, v48, v34
	v_fma_f32 v35, -v111, v92, v35
	v_fma_f32 v34, -v196, v49, v34
	v_fma_f32 v35, -v154, v90, v35
	v_fma_f32 v34, -v197, v50, v34
	v_fma_f32 v35, -v155, v88, v35
	v_fma_f32 v34, -v198, v51, v34
	v_fma_f32 v35, -v156, v86, v35
	v_fma_f32 v34, -v199, v78, v34
	v_fma_f32 v95, -v157, v84, v35
	ds_read_b128 v[102:105], v14 offset:14784
	ds_read_b128 v[106:109], v14 offset:14800
	ds_read_b128 v[154:157], v14 offset:14816
	ds_read_b128 v[158:161], v14 offset:14832
	ds_read_b128 v[162:165], v14 offset:14848
	ds_read_b128 v[166:169], v14 offset:14864
	ds_read_b128 v[170:173], v14 offset:14880
	ds_read_b128 v[174:177], v14 offset:14896
	ds_read_b128 v[182:185], v14 offset:14960
	ds_read_b128 v[186:189], v14 offset:14976
	ds_read_b128 v[190:193], v14 offset:14992
	ds_read_b128 v[194:197], v14 offset:15008
	s_waitcnt lgkmcnt(14)
	v_fma_f32 v33, -v134, v0, v33
	v_fma_f32 v33, -v135, v1, v33
	v_fma_f32 v33, -v136, v2, v33
	v_fma_f32 v33, -v137, v3, v33
	v_fma_f32 v34, -v112, v79, v34
	v_fma_f32 v33, -v138, v4, v33
	v_fma_f32 v34, -v113, v80, v34
	v_fma_f32 v33, -v139, v5, v33
	v_fma_f32 v34, -v114, v81, v34
	v_fma_f32 v33, -v140, v6, v33
	v_fma_f32 v34, -v115, v82, v34
	v_fma_f32 v33, -v141, v7, v33
	v_fma_f32 v34, -v116, v83, v34
	v_fma_f32 v33, -v142, v8, v33
	v_fma_f32 v34, -v117, v85, v34
	v_fma_f32 v33, -v143, v9, v33
	v_fma_f32 v34, -v118, v87, v34
	v_fma_f32 v33, -v144, v10, v33
	v_fma_f32 v34, -v119, v89, v34
	v_fma_f32 v33, -v145, v12, v33
	v_fma_f32 v34, -v120, v91, v34
	v_fma_f32 v33, -v146, v13, v33
	v_fma_f32 v34, -v121, v93, v34
	v_fma_f32 v33, -v147, v15, v33
	v_fma_f32 v34, -v122, v96, v34
	v_fma_f32 v33, -v148, v16, v33
	v_fma_f32 v34, -v123, v98, v34
	v_fma_f32 v33, -v149, v18, v33
	v_fma_f32 v34, -v124, v99, v34
	s_waitcnt lgkmcnt(13)
	v_fma_f32 v33, -v150, v19, v33
	v_fma_f32 v34, -v125, v97, v34
	v_fma_f32 v33, -v151, v25, v33
	v_fma_f32 v34, -v126, v94, v34
	v_fma_f32 v33, -v152, v27, v33
	v_fma_f32 v34, -v127, v92, v34
	v_fma_f32 v33, -v153, v40, v33
	v_fma_f32 v34, -v128, v90, v34
	s_waitcnt lgkmcnt(12)
	v_fma_f32 v33, -v178, v41, v33
	v_fma_f32 v34, -v129, v88, v34
	v_fma_f32 v33, -v179, v42, v33
	v_fma_f32 v34, -v130, v86, v34
	v_fma_f32 v33, -v180, v43, v33
	v_fma_f32 v34, -v131, v84, v34
	v_fma_f32 v33, -v181, v44, v33
	v_fma_f32 v100, -v132, v95, v34
	ds_read_b128 v[110:113], v14 offset:15024
	ds_read_b128 v[114:117], v14 offset:15040
	ds_read_b128 v[118:121], v14 offset:15056
	ds_read_b128 v[122:125], v14 offset:15072
	ds_read_b128 v[126:129], v14 offset:15088
	ds_read_b128 v[130:133], v14 offset:15104
	ds_read_b128 v[134:137], v14 offset:15120
	ds_read_b128 v[138:141], v14 offset:15136
	ds_read_b128 v[142:145], v14 offset:15152
	ds_read_b128 v[146:149], v14 offset:15168
	ds_read_b128 v[150:153], v14 offset:15232
	s_waitcnt lgkmcnt(14)
	ds_read_b128 v[176:179], v14 offset:15248
	v_fma_f32 v33, -v102, v45, v33
	v_fma_f32 v33, -v103, v46, v33
	v_fma_f32 v33, -v104, v47, v33
	v_fma_f32 v33, -v105, v48, v33
	v_fma_f32 v33, -v106, v49, v33
	v_fma_f32 v33, -v107, v50, v33
	v_fma_f32 v33, -v108, v51, v33
	v_fma_f32 v33, -v109, v78, v33
	v_fma_f32 v33, -v154, v79, v33
	v_fma_f32 v33, -v155, v80, v33
	v_fma_f32 v33, -v156, v81, v33
	v_fma_f32 v33, -v157, v82, v33
	v_fma_f32 v33, -v158, v83, v33
	v_fma_f32 v33, -v159, v85, v33
	v_fma_f32 v33, -v160, v87, v33
	v_fma_f32 v32, -v182, v0, v32
	v_fma_f32 v33, -v161, v89, v33
	v_fma_f32 v32, -v183, v1, v32
	v_fma_f32 v33, -v162, v91, v33
	v_fma_f32 v32, -v184, v2, v32
	v_fma_f32 v33, -v163, v93, v33
	v_fma_f32 v32, -v185, v3, v32
	v_fma_f32 v33, -v164, v96, v33
	s_waitcnt lgkmcnt(14)
	v_fma_f32 v32, -v186, v4, v32
	v_fma_f32 v33, -v165, v98, v33
	v_fma_f32 v32, -v187, v5, v32
	v_fma_f32 v33, -v166, v99, v33
	v_fma_f32 v32, -v188, v6, v32
	v_fma_f32 v33, -v167, v97, v33
	v_fma_f32 v32, -v189, v7, v32
	v_fma_f32 v33, -v168, v94, v33
	s_waitcnt lgkmcnt(13)
	v_fma_f32 v32, -v190, v8, v32
	v_fma_f32 v33, -v169, v92, v33
	v_fma_f32 v32, -v191, v9, v32
	v_fma_f32 v33, -v170, v90, v33
	v_fma_f32 v32, -v192, v10, v32
	v_fma_f32 v33, -v171, v88, v33
	v_fma_f32 v32, -v193, v12, v32
	v_fma_f32 v33, -v172, v86, v33
	s_waitcnt lgkmcnt(12)
	v_fma_f32 v32, -v194, v13, v32
	v_fma_f32 v33, -v173, v84, v33
	v_fma_f32 v32, -v195, v15, v32
	v_fma_f32 v33, -v174, v95, v33
	v_fma_f32 v32, -v196, v16, v32
	v_fma_f32 v101, -v175, v100, v33
	v_fma_f32 v102, -v197, v18, v32
	ds_read_b128 v[32:35], v14 offset:15264
	ds_read_b128 v[104:107], v14 offset:15280
	ds_read_b128 v[154:157], v14 offset:15296
	ds_read_b128 v[158:161], v14 offset:15312
	ds_read_b128 v[162:165], v14 offset:15328
	ds_read_b128 v[166:169], v14 offset:15344
	ds_read_b128 v[170:173], v14 offset:15360
	ds_read_b128 v[180:183], v14 offset:15376
	ds_read_b128 v[184:187], v14 offset:15392
	ds_read_b128 v[188:191], v14 offset:15408
	ds_read_b128 v[192:195], v14 offset:15424
	ds_read_b128 v[196:199], v14 offset:15440
	s_waitcnt lgkmcnt(14)
	v_fma_f32 v102, -v110, v19, v102
	v_fma_f32 v102, -v111, v25, v102
	v_fma_f32 v102, -v112, v27, v102
	v_fma_f32 v102, -v113, v40, v102
	v_fma_f32 v102, -v114, v41, v102
	v_fma_f32 v102, -v115, v42, v102
	v_fma_f32 v102, -v116, v43, v102
	v_fma_f32 v102, -v117, v44, v102
	v_fma_f32 v102, -v118, v45, v102
	v_fma_f32 v102, -v119, v46, v102
	v_fma_f32 v102, -v120, v47, v102
	v_fma_f32 v102, -v121, v48, v102
	v_fma_f32 v102, -v122, v49, v102
	v_fma_f32 v102, -v123, v50, v102
	v_fma_f32 v102, -v124, v51, v102
	v_fma_f32 v102, -v125, v78, v102
	v_fma_f32 v102, -v126, v79, v102
	v_fma_f32 v102, -v127, v80, v102
	v_fma_f32 v102, -v128, v81, v102
	v_fma_f32 v102, -v129, v82, v102
	v_fma_f32 v102, -v130, v83, v102
	v_fma_f32 v102, -v131, v85, v102
	v_fma_f32 v102, -v132, v87, v102
	v_fma_f32 v102, -v133, v89, v102
	v_fma_f32 v102, -v134, v91, v102
	v_fma_f32 v102, -v135, v93, v102
	v_fma_f32 v102, -v136, v96, v102
	v_fma_f32 v102, -v137, v98, v102
	v_fma_f32 v102, -v138, v99, v102
	v_fma_f32 v102, -v139, v97, v102
	v_fma_f32 v102, -v140, v94, v102
	s_waitcnt lgkmcnt(13)
	v_fma_f32 v31, -v150, v0, v31
	v_fma_f32 v102, -v141, v92, v102
	v_fma_f32 v31, -v151, v1, v31
	v_fma_f32 v102, -v142, v90, v102
	v_fma_f32 v31, -v152, v2, v31
	v_fma_f32 v102, -v143, v88, v102
	v_fma_f32 v31, -v153, v3, v31
	v_fma_f32 v102, -v144, v86, v102
	s_waitcnt lgkmcnt(12)
	v_fma_f32 v31, -v176, v4, v31
	v_fma_f32 v102, -v145, v84, v102
	v_fma_f32 v31, -v177, v5, v31
	v_fma_f32 v102, -v146, v95, v102
	v_fma_f32 v31, -v178, v6, v31
	v_fma_f32 v102, -v147, v100, v102
	v_fma_f32 v31, -v179, v7, v31
	v_fma_f32 v102, -v148, v101, v102
	ds_read_b128 v[108:111], v14 offset:15504
	ds_read_b128 v[112:115], v14 offset:15520
	ds_read_b128 v[116:119], v14 offset:15536
	ds_read_b128 v[120:123], v14 offset:15552
	ds_read_b128 v[124:127], v14 offset:15568
	ds_read_b128 v[128:131], v14 offset:15584
	ds_read_b128 v[132:135], v14 offset:15600
	ds_read_b128 v[136:139], v14 offset:15616
	ds_read_b128 v[140:143], v14 offset:15632
	ds_read_b128 v[144:147], v14 offset:15648
	ds_read_b128 v[148:151], v14 offset:15664
	ds_read_b128 v[174:177], v14 offset:15680
	s_waitcnt lgkmcnt(14)
	v_fma_f32 v31, -v32, v8, v31
	v_fma_f32 v31, -v33, v9, v31
	v_fma_f32 v31, -v34, v10, v31
	v_fma_f32 v31, -v35, v12, v31
	v_fma_f32 v31, -v104, v13, v31
	v_fma_f32 v31, -v105, v15, v31
	v_fma_f32 v31, -v106, v16, v31
	v_fma_f32 v31, -v107, v18, v31
	v_fma_f32 v31, -v154, v19, v31
	v_fma_f32 v31, -v155, v25, v31
	v_fma_f32 v31, -v156, v27, v31
	v_fma_f32 v31, -v157, v40, v31
	v_fma_f32 v31, -v158, v41, v31
	v_fma_f32 v31, -v159, v42, v31
	v_fma_f32 v31, -v160, v43, v31
	v_fma_f32 v31, -v161, v44, v31
	v_fma_f32 v31, -v162, v45, v31
	v_fma_f32 v31, -v163, v46, v31
	v_fma_f32 v31, -v164, v47, v31
	v_fma_f32 v31, -v165, v48, v31
	v_fma_f32 v31, -v166, v49, v31
	v_fma_f32 v31, -v167, v50, v31
	v_fma_f32 v31, -v168, v51, v31
	v_fma_f32 v31, -v169, v78, v31
	v_fma_f32 v31, -v170, v79, v31
	v_fma_f32 v31, -v171, v80, v31
	v_fma_f32 v31, -v172, v81, v31
	v_fma_f32 v31, -v173, v82, v31
	v_fma_f32 v31, -v180, v83, v31
	v_fma_f32 v31, -v181, v85, v31
	v_fma_f32 v31, -v182, v87, v31
	v_fma_f32 v31, -v183, v89, v31
	v_fma_f32 v31, -v184, v91, v31
	v_fma_f32 v31, -v185, v93, v31
	v_fma_f32 v31, -v186, v96, v31
	v_fma_f32 v31, -v187, v98, v31
	v_fma_f32 v31, -v188, v99, v31
	v_fma_f32 v31, -v189, v97, v31
	v_fma_f32 v31, -v190, v94, v31
	v_fma_f32 v31, -v191, v92, v31
	s_waitcnt lgkmcnt(13)
	v_fma_f32 v31, -v192, v90, v31
	v_fma_f32 v31, -v193, v88, v31
	v_fma_f32 v31, -v194, v86, v31
	v_fma_f32 v31, -v195, v84, v31
	s_waitcnt lgkmcnt(12)
	v_fma_f32 v31, -v196, v95, v31
	v_fma_f32 v31, -v197, v100, v31
	v_fma_f32 v31, -v198, v101, v31
	v_fma_f32 v103, -v199, v102, v31
	ds_read_b128 v[32:35], v14 offset:15696
	ds_read_b128 v[104:107], v14 offset:15712
	ds_read_b128 v[152:155], v14 offset:15728
	s_waitcnt lgkmcnt(0)
	ds_read_b128 v[154:157], v14 offset:15776
	ds_read_b128 v[158:161], v14 offset:15792
	ds_read_b128 v[162:165], v14 offset:15808
	ds_read_b128 v[166:169], v14 offset:15824
	ds_read_b128 v[170:173], v14 offset:15840
	ds_read_b128 v[178:181], v14 offset:15856
	ds_read_b128 v[182:185], v14 offset:15872
	ds_read_b128 v[186:189], v14 offset:15888
	ds_read_b128 v[190:193], v14 offset:15904
	v_fma_f32 v30, -v108, v0, v30
	v_fma_f32 v30, -v109, v1, v30
	v_fma_f32 v30, -v110, v2, v30
	v_fma_f32 v30, -v111, v3, v30
	v_fma_f32 v30, -v112, v4, v30
	v_fma_f32 v30, -v113, v5, v30
	v_fma_f32 v30, -v114, v6, v30
	v_fma_f32 v30, -v115, v7, v30
	v_fma_f32 v30, -v116, v8, v30
	v_fma_f32 v30, -v117, v9, v30
	v_fma_f32 v30, -v118, v10, v30
	v_fma_f32 v30, -v119, v12, v30
	v_fma_f32 v30, -v120, v13, v30
	v_fma_f32 v30, -v121, v15, v30
	v_fma_f32 v30, -v122, v16, v30
	v_fma_f32 v30, -v123, v18, v30
	v_fma_f32 v30, -v124, v19, v30
	v_fma_f32 v30, -v125, v25, v30
	v_fma_f32 v30, -v126, v27, v30
	v_fma_f32 v30, -v127, v40, v30
	v_fma_f32 v30, -v128, v41, v30
	v_fma_f32 v30, -v129, v42, v30
	v_fma_f32 v30, -v130, v43, v30
	v_fma_f32 v30, -v131, v44, v30
	v_fma_f32 v30, -v132, v45, v30
	v_fma_f32 v30, -v133, v46, v30
	v_fma_f32 v30, -v134, v47, v30
	v_fma_f32 v30, -v135, v48, v30
	v_fma_f32 v30, -v136, v49, v30
	v_fma_f32 v30, -v137, v50, v30
	v_fma_f32 v30, -v138, v51, v30
	v_fma_f32 v30, -v139, v78, v30
	v_fma_f32 v30, -v140, v79, v30
	v_fma_f32 v30, -v141, v80, v30
	v_fma_f32 v30, -v142, v81, v30
	v_fma_f32 v30, -v143, v82, v30
	v_fma_f32 v30, -v144, v83, v30
	v_fma_f32 v30, -v145, v85, v30
	v_fma_f32 v30, -v146, v87, v30
	v_fma_f32 v30, -v147, v89, v30
	v_fma_f32 v30, -v148, v91, v30
	v_fma_f32 v30, -v149, v93, v30
	v_fma_f32 v30, -v150, v96, v30
	v_fma_f32 v30, -v151, v98, v30
	v_fma_f32 v30, -v174, v99, v30
	v_fma_f32 v30, -v175, v97, v30
	v_fma_f32 v30, -v176, v94, v30
	v_fma_f32 v30, -v177, v92, v30
	ds_read_b128 v[108:111], v14 offset:15920
	ds_read_b128 v[112:115], v14 offset:15936
	ds_read_b128 v[116:119], v14 offset:15952
	ds_read_b128 v[120:123], v14 offset:15968
	ds_read_b128 v[124:127], v14 offset:15984
	ds_read_b128 v[128:131], v14 offset:16000
	s_waitcnt lgkmcnt(0)
	ds_read_b128 v[130:133], v14 offset:16048
	ds_read_b128 v[134:137], v14 offset:16064
	ds_read_b128 v[138:141], v14 offset:16080
	ds_read_b128 v[142:145], v14 offset:16096
	ds_read_b128 v[146:149], v14 offset:16112
	ds_read_b128 v[174:177], v14 offset:16128
	v_fma_f32 v29, -v154, v0, v29
	v_fma_f32 v29, -v155, v1, v29
	v_fma_f32 v29, -v156, v2, v29
	v_fma_f32 v29, -v157, v3, v29
	v_fma_f32 v29, -v158, v4, v29
	v_fma_f32 v29, -v159, v5, v29
	v_fma_f32 v29, -v160, v6, v29
	v_fma_f32 v29, -v161, v7, v29
	v_fma_f32 v29, -v162, v8, v29
	v_fma_f32 v29, -v163, v9, v29
	v_fma_f32 v29, -v164, v10, v29
	v_fma_f32 v29, -v165, v12, v29
	v_fma_f32 v29, -v166, v13, v29
	v_fma_f32 v29, -v167, v15, v29
	v_fma_f32 v29, -v168, v16, v29
	v_fma_f32 v29, -v169, v18, v29
	v_fma_f32 v29, -v170, v19, v29
	v_fma_f32 v29, -v171, v25, v29
	v_fma_f32 v29, -v172, v27, v29
	v_fma_f32 v29, -v173, v40, v29
	v_fma_f32 v29, -v178, v41, v29
	v_fma_f32 v29, -v179, v42, v29
	v_fma_f32 v29, -v180, v43, v29
	v_fma_f32 v29, -v181, v44, v29
	v_fma_f32 v29, -v182, v45, v29
	v_fma_f32 v29, -v183, v46, v29
	v_fma_f32 v29, -v184, v47, v29
	v_fma_f32 v29, -v185, v48, v29
	v_fma_f32 v30, -v32, v90, v30
	v_fma_f32 v29, -v186, v49, v29
	v_fma_f32 v30, -v33, v88, v30
	v_fma_f32 v29, -v187, v50, v29
	v_fma_f32 v30, -v34, v86, v30
	v_fma_f32 v29, -v188, v51, v29
	v_fma_f32 v30, -v35, v84, v30
	v_fma_f32 v29, -v189, v78, v29
	v_fma_f32 v30, -v104, v95, v30
	v_fma_f32 v29, -v190, v79, v29
	v_fma_f32 v30, -v105, v100, v30
	v_fma_f32 v29, -v191, v80, v29
	v_fma_f32 v30, -v106, v101, v30
	v_fma_f32 v29, -v192, v81, v29
	v_fma_f32 v30, -v107, v102, v30
	v_fma_f32 v29, -v193, v82, v29
	v_fma_f32 v198, -v152, v103, v30
	ds_read_b128 v[30:33], v14 offset:16144
	ds_read_b128 v[104:107], v14 offset:16160
	ds_read_b128 v[150:153], v14 offset:16176
	ds_read_b128 v[154:157], v14 offset:16192
	ds_read_b128 v[158:161], v14 offset:16208
	ds_read_b128 v[162:165], v14 offset:16224
	ds_read_b128 v[166:169], v14 offset:16240
	ds_read_b128 v[170:173], v14 offset:16256
	ds_read_b128 v[178:181], v14 offset:16272
	ds_read_b128 v[182:185], v14 offset:16320
	ds_read_b128 v[186:189], v14 offset:16336
	ds_read_b128 v[190:193], v14 offset:16352
	s_waitcnt lgkmcnt(14)
	v_fma_f32 v28, -v130, v0, v28
	v_fma_f32 v28, -v131, v1, v28
	v_fma_f32 v28, -v132, v2, v28
	v_fma_f32 v29, -v108, v83, v29
	v_fma_f32 v28, -v133, v3, v28
	v_fma_f32 v29, -v109, v85, v29
	v_fma_f32 v28, -v134, v4, v28
	v_fma_f32 v29, -v110, v87, v29
	v_fma_f32 v28, -v135, v5, v28
	v_fma_f32 v29, -v111, v89, v29
	v_fma_f32 v28, -v136, v6, v28
	v_fma_f32 v29, -v112, v91, v29
	v_fma_f32 v28, -v137, v7, v28
	v_fma_f32 v29, -v113, v93, v29
	v_fma_f32 v28, -v138, v8, v28
	v_fma_f32 v29, -v114, v96, v29
	v_fma_f32 v28, -v139, v9, v28
	v_fma_f32 v29, -v115, v98, v29
	v_fma_f32 v28, -v140, v10, v28
	v_fma_f32 v29, -v116, v99, v29
	v_fma_f32 v28, -v141, v12, v28
	v_fma_f32 v29, -v117, v97, v29
	v_fma_f32 v28, -v142, v13, v28
	v_fma_f32 v29, -v118, v94, v29
	v_fma_f32 v28, -v143, v15, v28
	v_fma_f32 v29, -v119, v92, v29
	v_fma_f32 v28, -v144, v16, v28
	v_fma_f32 v29, -v120, v90, v29
	v_fma_f32 v28, -v145, v18, v28
	v_fma_f32 v29, -v121, v88, v29
	s_waitcnt lgkmcnt(13)
	v_fma_f32 v28, -v146, v19, v28
	v_fma_f32 v29, -v122, v86, v29
	v_fma_f32 v28, -v147, v25, v28
	v_fma_f32 v29, -v123, v84, v29
	v_fma_f32 v28, -v148, v27, v28
	v_fma_f32 v29, -v124, v95, v29
	v_fma_f32 v28, -v149, v40, v28
	v_fma_f32 v29, -v125, v100, v29
	s_waitcnt lgkmcnt(12)
	v_fma_f32 v28, -v174, v41, v28
	v_fma_f32 v29, -v126, v101, v29
	v_fma_f32 v28, -v175, v42, v28
	v_fma_f32 v29, -v127, v102, v29
	v_fma_f32 v28, -v176, v43, v28
	v_fma_f32 v29, -v128, v103, v29
	v_fma_f32 v28, -v177, v44, v28
	v_fma_f32 v199, -v129, v198, v29
	ds_read_b128 v[108:111], v14 offset:16368
	ds_read_b128 v[112:115], v14 offset:16384
	ds_read_b128 v[116:119], v14 offset:16400
	ds_read_b128 v[120:123], v14 offset:16416
	ds_read_b128 v[124:127], v14 offset:16432
	ds_read_b128 v[128:131], v14 offset:16448
	ds_read_b128 v[132:135], v14 offset:16464
	ds_read_b128 v[136:139], v14 offset:16480
	ds_read_b128 v[140:143], v14 offset:16496
	ds_read_b128 v[144:147], v14 offset:16512
	ds_read_b128 v[174:177], v14 offset:16528
	ds_read_b128 v[194:197], v14 offset:16544
	s_waitcnt lgkmcnt(14)
	v_fma_f32 v28, -v30, v45, v28
	v_fma_f32 v28, -v31, v46, v28
	v_fma_f32 v28, -v32, v47, v28
	v_fma_f32 v28, -v33, v48, v28
	v_fma_f32 v28, -v104, v49, v28
	v_fma_f32 v28, -v105, v50, v28
	v_fma_f32 v28, -v106, v51, v28
	v_fma_f32 v28, -v107, v78, v28
	v_fma_f32 v28, -v150, v79, v28
	v_fma_f32 v28, -v151, v80, v28
	v_fma_f32 v28, -v152, v81, v28
	v_fma_f32 v28, -v153, v82, v28
	v_fma_f32 v28, -v154, v83, v28
	v_fma_f32 v28, -v155, v85, v28
	v_fma_f32 v28, -v156, v87, v28
	v_fma_f32 v28, -v157, v89, v28
	v_fma_f32 v28, -v158, v91, v28
	v_fma_f32 v28, -v159, v93, v28
	v_fma_f32 v28, -v160, v96, v28
	v_fma_f32 v28, -v161, v98, v28
	v_fma_f32 v28, -v162, v99, v28
	v_fma_f32 v28, -v163, v97, v28
	v_fma_f32 v28, -v164, v94, v28
	v_fma_f32 v26, -v182, v0, v26
	v_fma_f32 v28, -v165, v92, v28
	v_fma_f32 v26, -v183, v1, v26
	v_fma_f32 v28, -v166, v90, v28
	v_fma_f32 v26, -v184, v2, v26
	v_fma_f32 v28, -v167, v88, v28
	v_fma_f32 v26, -v185, v3, v26
	v_fma_f32 v28, -v168, v86, v28
	s_waitcnt lgkmcnt(13)
	v_fma_f32 v26, -v186, v4, v26
	v_fma_f32 v28, -v169, v84, v28
	v_fma_f32 v26, -v187, v5, v26
	v_fma_f32 v28, -v170, v95, v28
	v_fma_f32 v26, -v188, v6, v26
	v_fma_f32 v28, -v171, v100, v28
	v_fma_f32 v26, -v189, v7, v26
	v_fma_f32 v28, -v172, v101, v28
	s_waitcnt lgkmcnt(12)
	v_fma_f32 v26, -v190, v8, v26
	v_fma_f32 v28, -v173, v102, v28
	v_fma_f32 v26, -v191, v9, v26
	v_fma_f32 v28, -v178, v103, v28
	v_fma_f32 v26, -v192, v10, v26
	v_fma_f32 v28, -v179, v198, v28
	v_fma_f32 v26, -v193, v12, v26
	v_fma_f32 v200, -v180, v199, v28
	ds_read_b128 v[28:31], v14 offset:16592
	ds_read_b128 v[32:35], v14 offset:16608
	ds_read_b128 v[104:107], v14 offset:16624
	ds_read_b128 v[148:151], v14 offset:16640
	ds_read_b128 v[152:155], v14 offset:16656
	ds_read_b128 v[156:159], v14 offset:16672
	ds_read_b128 v[160:163], v14 offset:16688
	ds_read_b128 v[164:167], v14 offset:16704
	ds_read_b128 v[168:171], v14 offset:16720
	ds_read_b128 v[178:181], v14 offset:16736
	ds_read_b128 v[182:185], v14 offset:16752
	ds_read_b128 v[186:189], v14 offset:16768
	s_waitcnt lgkmcnt(14)
	v_fma_f32 v26, -v108, v13, v26
	v_fma_f32 v26, -v109, v15, v26
	v_fma_f32 v26, -v110, v16, v26
	v_fma_f32 v26, -v111, v18, v26
	v_fma_f32 v26, -v112, v19, v26
	v_fma_f32 v26, -v113, v25, v26
	v_fma_f32 v26, -v114, v27, v26
	v_fma_f32 v26, -v115, v40, v26
	v_fma_f32 v26, -v116, v41, v26
	v_fma_f32 v26, -v117, v42, v26
	v_fma_f32 v26, -v118, v43, v26
	v_fma_f32 v26, -v119, v44, v26
	v_fma_f32 v26, -v120, v45, v26
	v_fma_f32 v26, -v121, v46, v26
	v_fma_f32 v26, -v122, v47, v26
	v_fma_f32 v26, -v123, v48, v26
	v_fma_f32 v26, -v124, v49, v26
	v_fma_f32 v26, -v125, v50, v26
	v_fma_f32 v26, -v126, v51, v26
	v_fma_f32 v26, -v127, v78, v26
	v_fma_f32 v26, -v128, v79, v26
	v_fma_f32 v26, -v129, v80, v26
	v_fma_f32 v26, -v130, v81, v26
	v_fma_f32 v26, -v131, v82, v26
	v_fma_f32 v26, -v132, v83, v26
	v_fma_f32 v26, -v133, v85, v26
	v_fma_f32 v26, -v134, v87, v26
	v_fma_f32 v26, -v135, v89, v26
	v_fma_f32 v26, -v136, v91, v26
	v_fma_f32 v26, -v137, v93, v26
	v_fma_f32 v26, -v138, v96, v26
	v_fma_f32 v26, -v139, v98, v26
	v_fma_f32 v26, -v140, v99, v26
	v_fma_f32 v26, -v141, v97, v26
	v_fma_f32 v26, -v142, v94, v26
	v_fma_f32 v26, -v143, v92, v26
	v_fma_f32 v26, -v144, v90, v26
	v_fma_f32 v26, -v145, v88, v26
	v_fma_f32 v26, -v146, v86, v26
	v_fma_f32 v26, -v147, v84, v26
	s_waitcnt lgkmcnt(13)
	v_fma_f32 v26, -v174, v95, v26
	v_fma_f32 v26, -v175, v100, v26
	v_fma_f32 v26, -v176, v101, v26
	v_fma_f32 v26, -v177, v102, v26
	s_waitcnt lgkmcnt(12)
	v_fma_f32 v26, -v194, v103, v26
	v_fma_f32 v26, -v195, v198, v26
	v_fma_f32 v26, -v196, v199, v26
	v_fma_f32 v194, -v197, v200, v26
	ds_read_b128 v[108:111], v14 offset:16784
	ds_read_b128 v[112:115], v14 offset:16800
	ds_read_b128 v[116:119], v14 offset:16816
	ds_read_b128 v[120:123], v14 offset:16832
	s_waitcnt lgkmcnt(0)
	ds_read_b128 v[122:125], v14 offset:16864
	ds_read_b128 v[126:129], v14 offset:16880
	ds_read_b128 v[130:133], v14 offset:16896
	ds_read_b128 v[134:137], v14 offset:16912
	ds_read_b128 v[138:141], v14 offset:16928
	ds_read_b128 v[142:145], v14 offset:16944
	ds_read_b128 v[172:175], v14 offset:16960
	ds_read_b128 v[190:193], v14 offset:16976
	v_fma_f32 v24, -v28, v0, v24
	v_fma_f32 v24, -v29, v1, v24
	v_fma_f32 v24, -v30, v2, v24
	v_fma_f32 v24, -v31, v3, v24
	v_fma_f32 v24, -v32, v4, v24
	v_fma_f32 v24, -v33, v5, v24
	v_fma_f32 v24, -v34, v6, v24
	v_fma_f32 v24, -v35, v7, v24
	v_fma_f32 v24, -v104, v8, v24
	v_fma_f32 v24, -v105, v9, v24
	v_fma_f32 v24, -v106, v10, v24
	v_fma_f32 v24, -v107, v12, v24
	v_fma_f32 v24, -v148, v13, v24
	v_fma_f32 v24, -v149, v15, v24
	v_fma_f32 v24, -v150, v16, v24
	v_fma_f32 v24, -v151, v18, v24
	v_fma_f32 v24, -v152, v19, v24
	v_fma_f32 v24, -v153, v25, v24
	v_fma_f32 v24, -v154, v27, v24
	v_fma_f32 v24, -v155, v40, v24
	v_fma_f32 v24, -v156, v41, v24
	v_fma_f32 v24, -v157, v42, v24
	v_fma_f32 v24, -v158, v43, v24
	v_fma_f32 v24, -v159, v44, v24
	v_fma_f32 v24, -v160, v45, v24
	v_fma_f32 v24, -v161, v46, v24
	v_fma_f32 v24, -v162, v47, v24
	v_fma_f32 v24, -v163, v48, v24
	v_fma_f32 v24, -v164, v49, v24
	v_fma_f32 v24, -v165, v50, v24
	v_fma_f32 v24, -v166, v51, v24
	v_fma_f32 v24, -v167, v78, v24
	v_fma_f32 v24, -v168, v79, v24
	v_fma_f32 v24, -v169, v80, v24
	v_fma_f32 v24, -v170, v81, v24
	v_fma_f32 v24, -v171, v82, v24
	v_fma_f32 v24, -v178, v83, v24
	v_fma_f32 v24, -v179, v85, v24
	v_fma_f32 v24, -v180, v87, v24
	v_fma_f32 v24, -v181, v89, v24
	v_fma_f32 v24, -v182, v91, v24
	v_fma_f32 v24, -v183, v93, v24
	v_fma_f32 v24, -v184, v96, v24
	v_fma_f32 v24, -v185, v98, v24
	v_fma_f32 v24, -v186, v99, v24
	v_fma_f32 v24, -v187, v97, v24
	v_fma_f32 v24, -v188, v94, v24
	v_fma_f32 v24, -v189, v92, v24
	ds_read_b128 v[28:31], v14 offset:16992
	ds_read_b128 v[32:35], v14 offset:17008
	ds_read_b128 v[104:107], v14 offset:17024
	ds_read_b128 v[146:149], v14 offset:17040
	ds_read_b128 v[150:153], v14 offset:17056
	ds_read_b128 v[154:157], v14 offset:17072
	ds_read_b128 v[158:161], v14 offset:17088
	ds_read_b128 v[162:165], v14 offset:17104
	s_waitcnt lgkmcnt(0)
	ds_read_b128 v[164:167], v14 offset:17136
	ds_read_b128 v[168:171], v14 offset:17152
	ds_read_b128 v[176:179], v14 offset:17168
	ds_read_b128 v[180:183], v14 offset:17184
	v_fma_f32 v17, -v122, v0, v17
	v_fma_f32 v17, -v123, v1, v17
	v_fma_f32 v17, -v124, v2, v17
	v_fma_f32 v17, -v125, v3, v17
	v_fma_f32 v17, -v126, v4, v17
	v_fma_f32 v17, -v127, v5, v17
	v_fma_f32 v17, -v128, v6, v17
	v_fma_f32 v17, -v129, v7, v17
	v_fma_f32 v17, -v130, v8, v17
	v_fma_f32 v17, -v131, v9, v17
	v_fma_f32 v17, -v132, v10, v17
	v_fma_f32 v17, -v133, v12, v17
	v_fma_f32 v17, -v134, v13, v17
	v_fma_f32 v17, -v135, v15, v17
	v_fma_f32 v17, -v136, v16, v17
	v_fma_f32 v17, -v137, v18, v17
	v_fma_f32 v17, -v138, v19, v17
	v_fma_f32 v17, -v139, v25, v17
	v_fma_f32 v17, -v140, v27, v17
	v_fma_f32 v17, -v141, v40, v17
	v_fma_f32 v24, -v108, v90, v24
	v_fma_f32 v17, -v142, v41, v17
	v_fma_f32 v24, -v109, v88, v24
	v_fma_f32 v17, -v143, v42, v17
	v_fma_f32 v24, -v110, v86, v24
	v_fma_f32 v17, -v144, v43, v17
	v_fma_f32 v24, -v111, v84, v24
	v_fma_f32 v17, -v145, v44, v17
	v_fma_f32 v24, -v112, v95, v24
	v_fma_f32 v17, -v172, v45, v17
	v_fma_f32 v24, -v113, v100, v24
	v_fma_f32 v17, -v173, v46, v17
	v_fma_f32 v24, -v114, v101, v24
	v_fma_f32 v17, -v174, v47, v17
	v_fma_f32 v24, -v115, v102, v24
	v_fma_f32 v17, -v175, v48, v17
	v_fma_f32 v24, -v116, v103, v24
	v_fma_f32 v17, -v190, v49, v17
	v_fma_f32 v24, -v117, v198, v24
	v_fma_f32 v17, -v191, v50, v17
	v_fma_f32 v24, -v118, v199, v24
	v_fma_f32 v17, -v192, v51, v17
	v_fma_f32 v24, -v119, v200, v24
	v_fma_f32 v17, -v193, v78, v17
	v_fma_f32 v195, -v120, v194, v24
	ds_read_b128 v[108:111], v14 offset:17200
	ds_read_b128 v[112:115], v14 offset:17216
	ds_read_b128 v[116:119], v14 offset:17232
	ds_read_b128 v[120:123], v14 offset:17248
	ds_read_b128 v[124:127], v14 offset:17264
	ds_read_b128 v[128:131], v14 offset:17280
	ds_read_b128 v[132:135], v14 offset:17296
	ds_read_b128 v[136:139], v14 offset:17312
	ds_read_b128 v[140:143], v14 offset:17328
	ds_read_b128 v[172:175], v14 offset:17344
	ds_read_b128 v[184:187], v14 offset:17360
	ds_read_b128 v[188:191], v14 offset:17376
	v_fma_f32 v14, -v28, v79, v17
	v_fma_f32 v14, -v29, v80, v14
	v_fma_f32 v14, -v30, v81, v14
	v_fma_f32 v14, -v31, v82, v14
	v_fma_f32 v14, -v32, v83, v14
	v_fma_f32 v14, -v33, v85, v14
	v_fma_f32 v14, -v34, v87, v14
	v_fma_f32 v14, -v35, v89, v14
	v_fma_f32 v14, -v104, v91, v14
	v_fma_f32 v14, -v105, v93, v14
	v_fma_f32 v14, -v106, v96, v14
	v_fma_f32 v14, -v107, v98, v14
	v_fma_f32 v14, -v146, v99, v14
	v_fma_f32 v14, -v147, v97, v14
	s_waitcnt lgkmcnt(14)
	v_fma_f32 v11, -v164, v0, v11
	v_fma_f32 v14, -v148, v94, v14
	v_fma_f32 v11, -v165, v1, v11
	v_fma_f32 v14, -v149, v92, v14
	v_fma_f32 v11, -v166, v2, v11
	v_fma_f32 v14, -v150, v90, v14
	v_fma_f32 v11, -v167, v3, v11
	v_fma_f32 v14, -v151, v88, v14
	v_fma_f32 v11, -v168, v4, v11
	v_fma_f32 v14, -v152, v86, v14
	v_fma_f32 v11, -v169, v5, v11
	v_fma_f32 v14, -v153, v84, v14
	v_fma_f32 v11, -v170, v6, v11
	v_fma_f32 v14, -v154, v95, v14
	v_fma_f32 v11, -v171, v7, v11
	v_fma_f32 v14, -v155, v100, v14
	s_waitcnt lgkmcnt(13)
	v_fma_f32 v11, -v176, v8, v11
	v_fma_f32 v14, -v156, v101, v14
	v_fma_f32 v11, -v177, v9, v11
	v_fma_f32 v14, -v157, v102, v14
	v_fma_f32 v11, -v178, v10, v11
	v_fma_f32 v14, -v158, v103, v14
	v_fma_f32 v11, -v179, v12, v11
	v_fma_f32 v14, -v159, v198, v14
	s_waitcnt lgkmcnt(12)
	v_fma_f32 v11, -v180, v13, v11
	v_fma_f32 v14, -v160, v199, v14
	v_fma_f32 v11, -v181, v15, v11
	v_fma_f32 v14, -v161, v200, v14
	v_fma_f32 v11, -v182, v16, v11
	v_fma_f32 v14, -v162, v194, v14
	v_fma_f32 v11, -v183, v18, v11
	v_fma_f32 v104, -v163, v195, v14
	s_waitcnt lgkmcnt(11)
	v_fma_f32 v11, -v108, v19, v11
	v_fma_f32 v11, -v109, v25, v11
	v_fma_f32 v11, -v110, v27, v11
	v_fma_f32 v11, -v111, v40, v11
	s_waitcnt lgkmcnt(10)
	v_fma_f32 v11, -v112, v41, v11
	v_fma_f32 v11, -v113, v42, v11
	v_fma_f32 v11, -v114, v43, v11
	v_fma_f32 v11, -v115, v44, v11
	s_waitcnt lgkmcnt(9)
	v_fma_f32 v11, -v116, v45, v11
	v_fma_f32 v11, -v117, v46, v11
	v_fma_f32 v11, -v118, v47, v11
	v_fma_f32 v11, -v119, v48, v11
	s_waitcnt lgkmcnt(8)
	v_fma_f32 v11, -v120, v49, v11
	v_fma_f32 v11, -v121, v50, v11
	v_fma_f32 v11, -v122, v51, v11
	v_fma_f32 v11, -v123, v78, v11
	s_waitcnt lgkmcnt(7)
	v_fma_f32 v11, -v124, v79, v11
	v_fma_f32 v11, -v125, v80, v11
	v_fma_f32 v11, -v126, v81, v11
	v_fma_f32 v11, -v127, v82, v11
	s_waitcnt lgkmcnt(6)
	v_fma_f32 v11, -v128, v83, v11
	v_fma_f32 v11, -v129, v85, v11
	v_fma_f32 v11, -v130, v87, v11
	v_fma_f32 v11, -v131, v89, v11
	s_waitcnt lgkmcnt(5)
	v_fma_f32 v11, -v132, v91, v11
	v_fma_f32 v11, -v133, v93, v11
	v_fma_f32 v11, -v134, v96, v11
	v_fma_f32 v11, -v135, v98, v11
	s_waitcnt lgkmcnt(4)
	v_fma_f32 v11, -v136, v99, v11
	v_fma_f32 v11, -v137, v97, v11
	v_fma_f32 v11, -v138, v94, v11
	v_fma_f32 v11, -v139, v92, v11
	s_waitcnt lgkmcnt(3)
	v_fma_f32 v11, -v140, v90, v11
	v_fma_f32 v11, -v141, v88, v11
	v_fma_f32 v11, -v142, v86, v11
	v_fma_f32 v11, -v143, v84, v11
	s_waitcnt lgkmcnt(2)
	v_fma_f32 v11, -v172, v95, v11
	v_fma_f32 v11, -v173, v100, v11
	v_fma_f32 v11, -v174, v101, v11
	v_fma_f32 v11, -v175, v102, v11
	s_waitcnt lgkmcnt(1)
	v_fma_f32 v11, -v184, v103, v11
	v_fma_f32 v11, -v185, v198, v11
	v_fma_f32 v11, -v186, v199, v11
	v_fma_f32 v11, -v187, v200, v11
	s_waitcnt lgkmcnt(0)
	v_fma_f32 v11, -v188, v194, v11
	v_fma_f32 v11, -v189, v195, v11
	v_fma_f32 v105, -v190, v104, v11
	v_cvt_pk_bf16_f32 v35, v2, v3
	v_cvt_pk_bf16_f32 v34, v0, v1
	v_cvt_pk_bf16_f32 v32, v4, v5
	v_cvt_pk_bf16_f32 v33, v6, v7
	v_cvt_pk_bf16_f32 v30, v8, v9
	v_cvt_pk_bf16_f32 v31, v10, v12
	v_cvt_pk_bf16_f32 v28, v13, v15
	v_cvt_pk_bf16_f32 v29, v16, v18
	v_cvt_pk_bf16_f32 v26, v19, v25
	v_cvt_pk_bf16_f32 v27, v27, v40
	v_cvt_pk_bf16_f32 v24, v41, v42
	v_cvt_pk_bf16_f32 v25, v43, v44
	v_cvt_pk_bf16_f32 v18, v45, v46
	v_cvt_pk_bf16_f32 v19, v47, v48
	v_cvt_pk_bf16_f32 v16, v49, v50
	v_cvt_pk_bf16_f32 v17, v51, v78
	v_cvt_pk_bf16_f32 v14, v79, v80
	v_cvt_pk_bf16_f32 v15, v81, v82
	v_cvt_pk_bf16_f32 v12, v83, v85
	v_cvt_pk_bf16_f32 v13, v87, v89
	v_cvt_pk_bf16_f32 v10, v91, v93
	v_cvt_pk_bf16_f32 v11, v96, v98
	v_cvt_pk_bf16_f32 v8, v99, v97
	v_cvt_pk_bf16_f32 v9, v94, v92
	v_cvt_pk_bf16_f32 v6, v90, v88
	v_cvt_pk_bf16_f32 v7, v86, v84
	v_cvt_pk_bf16_f32 v4, v95, v100
	v_cvt_pk_bf16_f32 v5, v101, v102
	v_cvt_pk_bf16_f32 v2, v103, v198
	v_cvt_pk_bf16_f32 v3, v199, v200
	v_cvt_pk_bf16_f32 v0, v194, v195
	v_cvt_pk_bf16_f32 v1, v104, v105
	s_and_saveexec_b64 s[0:1], vcc
	s_xor_b64 s[0:1], exec, s[0:1]
	s_cbranch_execz .LBB0_419
	v_and_b32_e32 v39, 0x7ffffff0, v39
	v_lshlrev_b32_e32 v39, 1, v39
	v_lshlrev_b32_e32 v22, 1, v22
	v_add3_u32 v22, 0, v39, v22
	v_lshlrev_b32_e32 v39, 2, v77
	v_lshlrev_b32_e32 v38, 1, v38
	v_and_b32_e32 v39, 16, v39
	v_add3_u32 v22, v22, v38, v39
	ds_write_b16 v22, v34
	ds_write_b16_d16_hi v22, v34 offset:272
	ds_write_b16 v22, v35 offset:544
	ds_write_b16_d16_hi v22, v35 offset:816
	ds_write_b16 v22, v32 offset:1088
	ds_write_b16_d16_hi v22, v32 offset:1360
	ds_write_b16 v22, v33 offset:1632
	ds_write_b16_d16_hi v22, v33 offset:1904
	ds_write_b16 v22, v30 offset:2176
	ds_write_b16_d16_hi v22, v30 offset:2448
	ds_write_b16 v22, v31 offset:2720
	ds_write_b16_d16_hi v22, v31 offset:2992
	ds_write_b16 v22, v28 offset:3264
	ds_write_b16_d16_hi v22, v28 offset:3536
	ds_write_b16 v22, v29 offset:3808
	ds_write_b16_d16_hi v22, v29 offset:4080
	ds_write_b16 v22, v26 offset:4352
	ds_write_b16_d16_hi v22, v26 offset:4624
	ds_write_b16 v22, v27 offset:4896
	ds_write_b16_d16_hi v22, v27 offset:5168
	ds_write_b16 v22, v24 offset:5440
	ds_write_b16_d16_hi v22, v24 offset:5712
	ds_write_b16 v22, v25 offset:5984
	ds_write_b16_d16_hi v22, v25 offset:6256
	ds_write_b16 v22, v18 offset:6528
	ds_write_b16_d16_hi v22, v18 offset:6800
	ds_write_b16 v22, v19 offset:7072
	ds_write_b16_d16_hi v22, v19 offset:7344
	ds_write_b16 v22, v16 offset:7616
	ds_write_b16_d16_hi v22, v16 offset:7888
	ds_write_b16 v22, v17 offset:8160
	ds_write_b16_d16_hi v22, v17 offset:8432
	ds_write_b16 v22, v14 offset:8704
	ds_write_b16_d16_hi v22, v14 offset:8976
	ds_write_b16 v22, v15 offset:9248
	ds_write_b16_d16_hi v22, v15 offset:9520
	ds_write_b16 v22, v12 offset:9792
	ds_write_b16_d16_hi v22, v12 offset:10064
	ds_write_b16 v22, v13 offset:10336
	ds_write_b16_d16_hi v22, v13 offset:10608
	ds_write_b16 v22, v10 offset:10880
	ds_write_b16_d16_hi v22, v10 offset:11152
	ds_write_b16 v22, v11 offset:11424
	ds_write_b16_d16_hi v22, v11 offset:11696
	ds_write_b16 v22, v8 offset:11968
	ds_write_b16_d16_hi v22, v8 offset:12240
	ds_write_b16 v22, v9 offset:12512
	ds_write_b16_d16_hi v22, v9 offset:12784
	ds_write_b16 v22, v6 offset:13056
	ds_write_b16_d16_hi v22, v6 offset:13328
	ds_write_b16 v22, v7 offset:13600
	ds_write_b16_d16_hi v22, v7 offset:13872
	ds_write_b16 v22, v4 offset:14144
	ds_write_b16_d16_hi v22, v4 offset:14416
	ds_write_b16 v22, v5 offset:14688
	ds_write_b16_d16_hi v22, v5 offset:14960
	ds_write_b16 v22, v2 offset:15232
	ds_write_b16_d16_hi v22, v2 offset:15504
	ds_write_b16 v22, v3 offset:15776
	ds_write_b16_d16_hi v22, v3 offset:16048
	ds_write_b16 v22, v0 offset:16320
	ds_write_b16_d16_hi v22, v0 offset:16592
	ds_write_b16 v22, v1 offset:16864
	ds_write_b16_d16_hi v22, v1 offset:17136
